# GEMM mainloops: s_setprio 1 hoisted above the pre-MFMA barrier, redundant post-barrier lgkmcnt(0) dropped, s_setprio 0 moved below the post-MFMA barrier, mid-block setprio pair removed
# speedup vs baseline: 1.0129x; 1.0041x over previous
.LBB0_132:
	ds_read_b128 v[128:131], v179
	ds_read_b128 v[132:135], v179 offset:1024
	ds_read_b128 v[136:139], v179 offset:2048
	ds_read_b128 v[140:143], v179 offset:3072
	ds_read_b128 v[166:169], v180
	ds_read_b128 v[170:173], v180 offset:1024
	ds_read_b128 v[184:187], v180 offset:2048
	ds_read_b128 v[188:191], v180 offset:3072
	s_add_u32 s16, s74, 0xfff00080
	s_addc_u32 s17, s75, -1
	s_cmp_eq_u32 vcc_hi, 60
	s_cselect_b32 s79, s57, s17
	s_cselect_b32 s78, s95, s16
	s_cselect_b32 s77, s55, vcc_lo
	s_cselect_b32 s76, s96, s97
	v_lshl_add_u64 v[174:175], s[74:75], 0, v[158:159]
	s_add_i32 m0, s81, 0xc000
	ds_read_b128 v[192:195], v181
	ds_read_b128 v[196:199], v181 offset:1024
	ds_read_b128 v[200:203], v181 offset:2048
	ds_read_b128 v[206:209], v181 offset:3072
	ds_read_b128 v[210:213], v181 offset:4096
	ds_read_b128 v[214:217], v181 offset:5120
	ds_read_b128 v[218:221], v181 offset:6144
	ds_read_b128 v[222:225], v181 offset:7168
	global_load_lds_dwordx4 v[174:175], off
	v_lshl_add_u64 v[174:175], s[74:75], 0, v[160:161]
	s_add_i32 m0, s81, 0xe000
	s_nop 0
	global_load_lds_dwordx4 v[174:175], off
	s_waitcnt vmcnt(8)
	s_waitcnt lgkmcnt(0)
	s_setprio 1
	s_barrier
	v_mfma_f32_16x16x32_bf16 v[124:127], v[128:131], v[192:195], v[124:127]
	v_mfma_f32_16x16x32_bf16 v[120:123], v[136:139], v[192:195], v[120:123]
	v_mfma_f32_16x16x32_bf16 v[108:111], v[128:131], v[200:203], v[108:111]
	v_mfma_f32_16x16x32_bf16 v[104:107], v[136:139], v[200:203], v[104:107]
	v_mfma_f32_16x16x32_bf16 v[92:95], v[128:131], v[210:213], v[92:95]
	v_mfma_f32_16x16x32_bf16 v[88:91], v[136:139], v[210:213], v[88:91]
	v_mfma_f32_16x16x32_bf16 v[76:79], v[128:131], v[218:221], v[76:79]
	v_mfma_f32_16x16x32_bf16 v[72:75], v[136:139], v[218:221], v[72:75]
	v_mfma_f32_16x16x32_bf16 v[124:127], v[132:135], v[196:199], v[124:127]
	v_mfma_f32_16x16x32_bf16 v[120:123], v[140:143], v[196:199], v[120:123]
	v_mfma_f32_16x16x32_bf16 v[108:111], v[132:135], v[206:209], v[108:111]
	v_mfma_f32_16x16x32_bf16 v[104:107], v[140:143], v[206:209], v[104:107]
	v_mfma_f32_16x16x32_bf16 v[92:95], v[132:135], v[214:217], v[92:95]
	v_mfma_f32_16x16x32_bf16 v[88:91], v[140:143], v[214:217], v[88:91]
	v_mfma_f32_16x16x32_bf16 v[76:79], v[132:135], v[222:225], v[76:79]
	v_mfma_f32_16x16x32_bf16 v[72:75], v[140:143], v[222:225], v[72:75]
	v_mfma_f32_16x16x32_bf16 v[116:119], v[166:169], v[192:195], v[116:119]
	v_mfma_f32_16x16x32_bf16 v[112:115], v[184:187], v[192:195], v[112:115]
	v_mfma_f32_16x16x32_bf16 v[100:103], v[166:169], v[200:203], v[100:103]
	v_mfma_f32_16x16x32_bf16 v[96:99], v[184:187], v[200:203], v[96:99]
	v_mfma_f32_16x16x32_bf16 v[84:87], v[166:169], v[210:213], v[84:87]
	v_mfma_f32_16x16x32_bf16 v[80:83], v[184:187], v[210:213], v[80:83]
	v_mfma_f32_16x16x32_bf16 v[68:71], v[166:169], v[218:221], v[68:71]
	v_mfma_f32_16x16x32_bf16 v[64:67], v[184:187], v[218:221], v[64:67]
	v_mfma_f32_16x16x32_bf16 v[116:119], v[170:173], v[196:199], v[116:119]
	v_mfma_f32_16x16x32_bf16 v[112:115], v[188:191], v[196:199], v[112:115]
	v_mfma_f32_16x16x32_bf16 v[100:103], v[170:173], v[206:209], v[100:103]
	v_mfma_f32_16x16x32_bf16 v[96:99], v[188:191], v[206:209], v[96:99]
	v_mfma_f32_16x16x32_bf16 v[84:87], v[170:173], v[214:217], v[84:87]
	v_mfma_f32_16x16x32_bf16 v[80:83], v[188:191], v[214:217], v[80:83]
	v_mfma_f32_16x16x32_bf16 v[68:71], v[170:173], v[222:225], v[68:71]
	v_mfma_f32_16x16x32_bf16 v[64:67], v[188:191], v[222:225], v[64:67]
	s_barrier
	s_setprio 0
	s_add_i32 s16, s93, s80
	v_lshl_add_u64 v[174:175], s[76:77], 0, v[146:147]
	s_mov_b32 m0, s16
	ds_read_b128 v[192:195], v181 offset:16384
	ds_read_b128 v[196:199], v181 offset:17408
	ds_read_b128 v[200:203], v181 offset:18432
	ds_read_b128 v[206:209], v181 offset:19456
	ds_read_b128 v[210:213], v181 offset:20480
	ds_read_b128 v[214:217], v181 offset:21504
	ds_read_b128 v[218:221], v181 offset:22528
	ds_read_b128 v[222:225], v181 offset:23552
	global_load_lds_dwordx4 v[174:175], off
	s_add_i32 m0, s16, 0x2000
	s_add_u32 s16, s76, 0x100000
	v_lshl_add_u64 v[228:229], s[76:77], 0, v[150:151]
	s_addc_u32 s17, s77, 0
	s_add_i32 s3, s94, s80
	global_load_lds_dwordx4 v[228:229], off
	v_lshl_add_u64 v[230:231], s[16:17], 0, v[146:147]
	s_mov_b32 m0, s3
	v_lshl_add_u64 v[232:233], s[78:79], 0, v[148:149]
	global_load_lds_dwordx4 v[230:231], off
	v_lshl_add_u64 v[230:231], s[16:17], 0, v[150:151]
	s_add_i32 m0, s3, 0x2000
	s_nop 0
	global_load_lds_dwordx4 v[230:231], off
	v_lshl_add_u64 v[230:231], s[78:79], 0, v[144:145]
	s_mov_b32 m0, s81
	s_nop 0
	global_load_lds_dwordx4 v[230:231], off
	s_mov_b32 m0, s82
	s_nop 0
	global_load_lds_dwordx4 v[232:233], off
	s_waitcnt vmcnt(8)
	s_waitcnt lgkmcnt(0)
	s_setprio 1
	s_barrier
	v_mfma_f32_16x16x32_bf16 v[60:63], v[128:131], v[192:195], v[60:63]
	v_mfma_f32_16x16x32_bf16 v[56:59], v[136:139], v[192:195], v[56:59]
	v_mfma_f32_16x16x32_bf16 v[44:47], v[128:131], v[200:203], v[44:47]
	v_mfma_f32_16x16x32_bf16 v[40:43], v[136:139], v[200:203], v[40:43]
	v_mfma_f32_16x16x32_bf16 v[28:31], v[128:131], v[210:213], v[28:31]
	v_mfma_f32_16x16x32_bf16 v[24:27], v[136:139], v[210:213], v[24:27]
	v_mfma_f32_16x16x32_bf16 v[12:15], v[128:131], v[218:221], v[12:15]
	v_mfma_f32_16x16x32_bf16 v[8:11], v[136:139], v[218:221], v[8:11]
	v_mfma_f32_16x16x32_bf16 v[60:63], v[132:135], v[196:199], v[60:63]
	v_mfma_f32_16x16x32_bf16 v[56:59], v[140:143], v[196:199], v[56:59]
	v_mfma_f32_16x16x32_bf16 v[44:47], v[132:135], v[206:209], v[44:47]
	v_mfma_f32_16x16x32_bf16 v[40:43], v[140:143], v[206:209], v[40:43]
	v_mfma_f32_16x16x32_bf16 v[28:31], v[132:135], v[214:217], v[28:31]
	v_mfma_f32_16x16x32_bf16 v[24:27], v[140:143], v[214:217], v[24:27]
	v_mfma_f32_16x16x32_bf16 v[12:15], v[132:135], v[222:225], v[12:15]
	v_mfma_f32_16x16x32_bf16 v[8:11], v[140:143], v[222:225], v[8:11]
	v_mfma_f32_16x16x32_bf16 v[52:55], v[166:169], v[192:195], v[52:55]
	v_mfma_f32_16x16x32_bf16 v[48:51], v[184:187], v[192:195], v[48:51]
	v_mfma_f32_16x16x32_bf16 v[36:39], v[166:169], v[200:203], v[36:39]
	v_mfma_f32_16x16x32_bf16 v[32:35], v[184:187], v[200:203], v[32:35]
	v_mfma_f32_16x16x32_bf16 v[20:23], v[166:169], v[210:213], v[20:23]
	v_mfma_f32_16x16x32_bf16 v[16:19], v[184:187], v[210:213], v[16:19]
	v_mfma_f32_16x16x32_bf16 v[4:7], v[166:169], v[218:221], v[4:7]
	v_mfma_f32_16x16x32_bf16 v[0:3], v[184:187], v[218:221], v[0:3]
	v_mfma_f32_16x16x32_bf16 v[52:55], v[170:173], v[196:199], v[52:55]
	v_mfma_f32_16x16x32_bf16 v[48:51], v[188:191], v[196:199], v[48:51]
	v_mfma_f32_16x16x32_bf16 v[36:39], v[170:173], v[206:209], v[36:39]
	v_mfma_f32_16x16x32_bf16 v[32:35], v[188:191], v[206:209], v[32:35]
	v_mfma_f32_16x16x32_bf16 v[20:23], v[170:173], v[214:217], v[20:23]
	v_mfma_f32_16x16x32_bf16 v[16:19], v[188:191], v[214:217], v[16:19]
	v_mfma_f32_16x16x32_bf16 v[4:7], v[170:173], v[222:225], v[4:7]
	v_mfma_f32_16x16x32_bf16 v[0:3], v[188:191], v[222:225], v[0:3]
	s_barrier
	s_setprio 0
	s_add_i32 s3, 0, 0x18000
	s_add_i32 s33, 0, 0x1c000
	v_add_u32_e32 v140, s3, v177
	v_add_u32_e32 v152, s33, v177
	ds_read_b128 v[128:131], v140
	ds_read_b128 v[132:135], v140 offset:1024
	ds_read_b128 v[136:139], v140 offset:2048
	ds_read_b128 v[140:143], v140 offset:3072
	ds_read_b128 v[166:169], v152
	ds_read_b128 v[170:173], v152 offset:1024
	ds_read_b128 v[184:187], v152 offset:2048
	ds_read_b128 v[188:191], v152 offset:3072
	s_add_u32 s16, s78, 0x100000
	s_addc_u32 s17, s79, 0
	s_mov_b32 m0, s83
	v_lshl_add_u64 v[234:235], s[16:17], 0, v[144:145]
	ds_read_b128 v[192:195], v181 offset:32768
	ds_read_b128 v[196:199], v181 offset:33792
	ds_read_b128 v[200:203], v181 offset:34816
	ds_read_b128 v[206:209], v181 offset:35840
	ds_read_b128 v[210:213], v181 offset:36864
	ds_read_b128 v[214:217], v181 offset:37888
	ds_read_b128 v[218:221], v181 offset:38912
	ds_read_b128 v[222:225], v181 offset:39936
	global_load_lds_dwordx4 v[234:235], off
	v_lshl_add_u64 v[234:235], s[16:17], 0, v[148:149]
	s_mov_b32 m0, s84
	s_nop 0
	global_load_lds_dwordx4 v[234:235], off
	s_waitcnt vmcnt(8)
	s_waitcnt lgkmcnt(0)
	s_setprio 1
	s_barrier
	v_mfma_f32_16x16x32_bf16 v[124:127], v[128:131], v[192:195], v[124:127]
	v_mfma_f32_16x16x32_bf16 v[120:123], v[136:139], v[192:195], v[120:123]
	v_mfma_f32_16x16x32_bf16 v[108:111], v[128:131], v[200:203], v[108:111]
	v_mfma_f32_16x16x32_bf16 v[104:107], v[136:139], v[200:203], v[104:107]
	v_mfma_f32_16x16x32_bf16 v[92:95], v[128:131], v[210:213], v[92:95]
	v_mfma_f32_16x16x32_bf16 v[88:91], v[136:139], v[210:213], v[88:91]
	v_mfma_f32_16x16x32_bf16 v[76:79], v[128:131], v[218:221], v[76:79]
	v_mfma_f32_16x16x32_bf16 v[72:75], v[136:139], v[218:221], v[72:75]
	v_mfma_f32_16x16x32_bf16 v[124:127], v[132:135], v[196:199], v[124:127]
	v_mfma_f32_16x16x32_bf16 v[120:123], v[140:143], v[196:199], v[120:123]
	v_mfma_f32_16x16x32_bf16 v[108:111], v[132:135], v[206:209], v[108:111]
	v_mfma_f32_16x16x32_bf16 v[104:107], v[140:143], v[206:209], v[104:107]
	v_mfma_f32_16x16x32_bf16 v[92:95], v[132:135], v[214:217], v[92:95]
	v_mfma_f32_16x16x32_bf16 v[88:91], v[140:143], v[214:217], v[88:91]
	v_mfma_f32_16x16x32_bf16 v[76:79], v[132:135], v[222:225], v[76:79]
	v_mfma_f32_16x16x32_bf16 v[72:75], v[140:143], v[222:225], v[72:75]
	v_mfma_f32_16x16x32_bf16 v[116:119], v[166:169], v[192:195], v[116:119]
	v_mfma_f32_16x16x32_bf16 v[112:115], v[184:187], v[192:195], v[112:115]
	v_mfma_f32_16x16x32_bf16 v[100:103], v[166:169], v[200:203], v[100:103]
	v_mfma_f32_16x16x32_bf16 v[96:99], v[184:187], v[200:203], v[96:99]
	v_mfma_f32_16x16x32_bf16 v[84:87], v[166:169], v[210:213], v[84:87]
	v_mfma_f32_16x16x32_bf16 v[80:83], v[184:187], v[210:213], v[80:83]
	v_mfma_f32_16x16x32_bf16 v[68:71], v[166:169], v[218:221], v[68:71]
	v_mfma_f32_16x16x32_bf16 v[64:67], v[184:187], v[218:221], v[64:67]
	v_mfma_f32_16x16x32_bf16 v[116:119], v[170:173], v[196:199], v[116:119]
	v_mfma_f32_16x16x32_bf16 v[112:115], v[188:191], v[196:199], v[112:115]
	v_mfma_f32_16x16x32_bf16 v[100:103], v[170:173], v[206:209], v[100:103]
	v_mfma_f32_16x16x32_bf16 v[96:99], v[188:191], v[206:209], v[96:99]
	v_mfma_f32_16x16x32_bf16 v[84:87], v[170:173], v[214:217], v[84:87]
	v_mfma_f32_16x16x32_bf16 v[80:83], v[188:191], v[214:217], v[80:83]
	v_mfma_f32_16x16x32_bf16 v[68:71], v[170:173], v[222:225], v[68:71]
	v_mfma_f32_16x16x32_bf16 v[64:67], v[188:191], v[222:225], v[64:67]
	s_barrier
	s_setprio 0
	s_add_i32 s3, s3, s80
	v_lshl_add_u64 v[174:175], v[174:175], 0, s[42:43]
	s_mov_b32 m0, s3
	ds_read_b128 v[192:195], v181 offset:49152
	ds_read_b128 v[196:199], v181 offset:50176
	ds_read_b128 v[200:203], v181 offset:51200
	ds_read_b128 v[206:209], v181 offset:52224
	ds_read_b128 v[210:213], v181 offset:53248
	ds_read_b128 v[214:217], v181 offset:54272
	ds_read_b128 v[218:221], v181 offset:55296
	ds_read_b128 v[222:225], v181 offset:56320
	global_load_lds_dwordx4 v[174:175], off
	s_add_i32 m0, s3, 0x2000
	s_add_u32 s16, s76, 0x100800
	v_lshl_add_u64 v[174:175], v[228:229], 0, s[42:43]
	s_addc_u32 s17, s77, 0
	s_add_i32 s3, s33, s80
	global_load_lds_dwordx4 v[174:175], off
	v_lshl_add_u64 v[174:175], s[16:17], 0, v[146:147]
	s_mov_b32 m0, s3
	s_nop 0
	global_load_lds_dwordx4 v[174:175], off
	v_lshl_add_u64 v[174:175], s[16:17], 0, v[150:151]
	s_add_i32 m0, s3, 0x2000
	s_nop 0
	global_load_lds_dwordx4 v[174:175], off
	v_lshl_add_u64 v[174:175], v[230:231], 0, s[44:45]
	s_mov_b32 m0, s86
	s_nop 0
	global_load_lds_dwordx4 v[174:175], off
	v_lshl_add_u64 v[174:175], v[232:233], 0, s[44:45]
	s_mov_b32 m0, s87
	s_nop 0
	global_load_lds_dwordx4 v[174:175], off
	s_waitcnt vmcnt(8)
	s_waitcnt lgkmcnt(0)
	s_setprio 1
	s_barrier
	v_mfma_f32_16x16x32_bf16 v[60:63], v[128:131], v[192:195], v[60:63]
	v_mfma_f32_16x16x32_bf16 v[56:59], v[136:139], v[192:195], v[56:59]
	v_mfma_f32_16x16x32_bf16 v[44:47], v[128:131], v[200:203], v[44:47]
	v_mfma_f32_16x16x32_bf16 v[40:43], v[136:139], v[200:203], v[40:43]
	v_mfma_f32_16x16x32_bf16 v[28:31], v[128:131], v[210:213], v[28:31]
	v_mfma_f32_16x16x32_bf16 v[24:27], v[136:139], v[210:213], v[24:27]
	v_mfma_f32_16x16x32_bf16 v[12:15], v[128:131], v[218:221], v[12:15]
	v_mfma_f32_16x16x32_bf16 v[8:11], v[136:139], v[218:221], v[8:11]
	v_mfma_f32_16x16x32_bf16 v[60:63], v[132:135], v[196:199], v[60:63]
	v_mfma_f32_16x16x32_bf16 v[56:59], v[140:143], v[196:199], v[56:59]
	v_mfma_f32_16x16x32_bf16 v[44:47], v[132:135], v[206:209], v[44:47]
	v_mfma_f32_16x16x32_bf16 v[40:43], v[140:143], v[206:209], v[40:43]
	v_mfma_f32_16x16x32_bf16 v[28:31], v[132:135], v[214:217], v[28:31]
	v_mfma_f32_16x16x32_bf16 v[24:27], v[140:143], v[214:217], v[24:27]
	v_mfma_f32_16x16x32_bf16 v[12:15], v[132:135], v[222:225], v[12:15]
	v_mfma_f32_16x16x32_bf16 v[8:11], v[140:143], v[222:225], v[8:11]
	v_mfma_f32_16x16x32_bf16 v[52:55], v[166:169], v[192:195], v[52:55]
	v_mfma_f32_16x16x32_bf16 v[48:51], v[184:187], v[192:195], v[48:51]
	v_mfma_f32_16x16x32_bf16 v[36:39], v[166:169], v[200:203], v[36:39]
	v_mfma_f32_16x16x32_bf16 v[32:35], v[184:187], v[200:203], v[32:35]
	v_mfma_f32_16x16x32_bf16 v[20:23], v[166:169], v[210:213], v[20:23]
	v_mfma_f32_16x16x32_bf16 v[16:19], v[184:187], v[210:213], v[16:19]
	v_mfma_f32_16x16x32_bf16 v[4:7], v[166:169], v[218:221], v[4:7]
	v_mfma_f32_16x16x32_bf16 v[0:3], v[184:187], v[218:221], v[0:3]
	v_mfma_f32_16x16x32_bf16 v[52:55], v[170:173], v[196:199], v[52:55]
	v_mfma_f32_16x16x32_bf16 v[48:51], v[188:191], v[196:199], v[48:51]
	v_mfma_f32_16x16x32_bf16 v[36:39], v[170:173], v[206:209], v[36:39]
	v_mfma_f32_16x16x32_bf16 v[32:35], v[188:191], v[206:209], v[32:35]
	v_mfma_f32_16x16x32_bf16 v[20:23], v[170:173], v[214:217], v[20:23]
	v_mfma_f32_16x16x32_bf16 v[16:19], v[188:191], v[214:217], v[16:19]
	v_mfma_f32_16x16x32_bf16 v[4:7], v[170:173], v[222:225], v[4:7]
	v_mfma_f32_16x16x32_bf16 v[0:3], v[188:191], v[222:225], v[0:3]
	s_barrier
	s_setprio 0
	s_add_i32 vcc_hi, vcc_hi, 2
	s_add_u32 s97, s97, 0x1000
	s_addc_u32 vcc_lo, vcc_lo, 0
	s_add_u32 s74, s74, 0x100
	s_addc_u32 s75, s75, 0
	s_cmp_gt_u32 vcc_hi, 61
	s_cbranch_scc0 .LBB0_132
	s_and_b64 vcc, exec, s[46:47]
	s_cbranch_vccz .LBB0_135
	s_barrier

.LBB0_432:
	ds_read_b128 v[128:131], v161
	ds_read_b128 v[132:135], v161 offset:1024
	ds_read_b128 v[136:139], v161 offset:2048
	ds_read_b128 v[140:143], v161 offset:3072
	ds_read_b128 v[164:167], v162
	ds_read_b128 v[168:171], v162 offset:1024
	ds_read_b128 v[172:175], v162 offset:2048
	ds_read_b128 v[176:179], v162 offset:3072
	s_add_u32 s3, s70, 0xfff80080
	s_addc_u32 s16, s71, -1
	s_cmp_eq_u32 vcc_hi, 4
	s_cselect_b32 s75, s93, s16
	s_cselect_b32 s74, s94, s3
	s_cselect_b32 s73, s95, vcc_lo
	s_cselect_b32 s72, s96, s97
	v_lshl_add_u64 v[156:157], s[70:71], 0, v[152:153]
	s_add_i32 m0, s1, 0xc000
	ds_read_b128 v[180:183], v163
	ds_read_b128 v[184:187], v163 offset:1024
	ds_read_b128 v[188:191], v163 offset:2048
	ds_read_b128 v[192:195], v163 offset:3072
	ds_read_b128 v[196:199], v163 offset:4096
	ds_read_b128 v[200:203], v163 offset:5120
	ds_read_b128 v[206:209], v163 offset:6144
	ds_read_b128 v[210:213], v163 offset:7168
	global_load_lds_dwordx4 v[156:157], off
	v_lshl_add_u64 v[156:157], s[70:71], 0, v[154:155]
	s_add_i32 m0, s1, 0xe000
	s_nop 0
	global_load_lds_dwordx4 v[156:157], off
	s_waitcnt vmcnt(8)
	s_waitcnt lgkmcnt(0)
	s_setprio 1
	s_barrier
	v_mfma_f32_16x16x32_bf16 v[124:127], v[128:131], v[180:183], v[124:127]
	v_mfma_f32_16x16x32_bf16 v[120:123], v[136:139], v[180:183], v[120:123]
	v_mfma_f32_16x16x32_bf16 v[116:119], v[128:131], v[188:191], v[116:119]
	v_mfma_f32_16x16x32_bf16 v[112:115], v[136:139], v[188:191], v[112:115]
	v_mfma_f32_16x16x32_bf16 v[108:111], v[128:131], v[196:199], v[108:111]
	v_mfma_f32_16x16x32_bf16 v[100:103], v[136:139], v[196:199], v[100:103]
	v_mfma_f32_16x16x32_bf16 v[76:79], v[128:131], v[206:209], v[76:79]
	v_mfma_f32_16x16x32_bf16 v[72:75], v[136:139], v[206:209], v[72:75]
	v_mfma_f32_16x16x32_bf16 v[124:127], v[132:135], v[184:187], v[124:127]
	v_mfma_f32_16x16x32_bf16 v[120:123], v[140:143], v[184:187], v[120:123]
	v_mfma_f32_16x16x32_bf16 v[116:119], v[132:135], v[192:195], v[116:119]
	v_mfma_f32_16x16x32_bf16 v[112:115], v[140:143], v[192:195], v[112:115]
	v_mfma_f32_16x16x32_bf16 v[108:111], v[132:135], v[200:203], v[108:111]
	v_mfma_f32_16x16x32_bf16 v[100:103], v[140:143], v[200:203], v[100:103]
	v_mfma_f32_16x16x32_bf16 v[76:79], v[132:135], v[210:213], v[76:79]
	v_mfma_f32_16x16x32_bf16 v[72:75], v[140:143], v[210:213], v[72:75]
	v_mfma_f32_16x16x32_bf16 v[104:107], v[164:167], v[180:183], v[104:107]
	v_mfma_f32_16x16x32_bf16 v[96:99], v[172:175], v[180:183], v[96:99]
	v_mfma_f32_16x16x32_bf16 v[92:95], v[164:167], v[188:191], v[92:95]
	v_mfma_f32_16x16x32_bf16 v[88:91], v[172:175], v[188:191], v[88:91]
	v_mfma_f32_16x16x32_bf16 v[84:87], v[164:167], v[196:199], v[84:87]
	v_mfma_f32_16x16x32_bf16 v[80:83], v[172:175], v[196:199], v[80:83]
	v_mfma_f32_16x16x32_bf16 v[68:71], v[164:167], v[206:209], v[68:71]
	v_mfma_f32_16x16x32_bf16 v[64:67], v[172:175], v[206:209], v[64:67]
	v_mfma_f32_16x16x32_bf16 v[104:107], v[168:171], v[184:187], v[104:107]
	v_mfma_f32_16x16x32_bf16 v[96:99], v[176:179], v[184:187], v[96:99]
	v_mfma_f32_16x16x32_bf16 v[92:95], v[168:171], v[192:195], v[92:95]
	v_mfma_f32_16x16x32_bf16 v[88:91], v[176:179], v[192:195], v[88:91]
	v_mfma_f32_16x16x32_bf16 v[84:87], v[168:171], v[200:203], v[84:87]
	v_mfma_f32_16x16x32_bf16 v[80:83], v[176:179], v[200:203], v[80:83]
	v_mfma_f32_16x16x32_bf16 v[68:71], v[168:171], v[210:213], v[68:71]
	v_mfma_f32_16x16x32_bf16 v[64:67], v[176:179], v[210:213], v[64:67]
	s_barrier
	s_setprio 0
	s_add_i32 s3, s85, s19
	v_lshl_add_u64 v[156:157], s[72:73], 0, v[148:149]
	s_mov_b32 m0, s3
	ds_read_b128 v[180:183], v163 offset:16384
	ds_read_b128 v[184:187], v163 offset:17408
	ds_read_b128 v[188:191], v163 offset:18432
	ds_read_b128 v[192:195], v163 offset:19456
	ds_read_b128 v[196:199], v163 offset:20480
	ds_read_b128 v[200:203], v163 offset:21504
	ds_read_b128 v[206:209], v163 offset:22528
	ds_read_b128 v[210:213], v163 offset:23552
	global_load_lds_dwordx4 v[156:157], off
	s_add_i32 m0, s3, 0x2000
	s_add_u32 s16, s72, 0x20000
	v_lshl_add_u64 v[214:215], s[72:73], 0, v[144:145]
	s_addc_u32 s17, s73, 0
	s_add_i32 s3, s86, s19
	global_load_lds_dwordx4 v[214:215], off
	v_lshl_add_u64 v[216:217], s[16:17], 0, v[148:149]
	s_mov_b32 m0, s3
	v_lshl_add_u64 v[218:219], s[74:75], 0, v[146:147]
	global_load_lds_dwordx4 v[216:217], off
	v_lshl_add_u64 v[216:217], s[16:17], 0, v[144:145]
	s_add_i32 m0, s3, 0x2000
	s_nop 0
	global_load_lds_dwordx4 v[216:217], off
	v_lshl_add_u64 v[216:217], s[74:75], 0, v[150:151]
	s_mov_b32 m0, s1
	s_nop 0
	global_load_lds_dwordx4 v[216:217], off
	s_mov_b32 m0, s79
	s_nop 0
	global_load_lds_dwordx4 v[218:219], off
	s_waitcnt vmcnt(8)
	s_waitcnt lgkmcnt(0)
	s_setprio 1
	s_barrier
	v_mfma_f32_16x16x32_bf16 v[60:63], v[128:131], v[180:183], v[60:63]
	v_mfma_f32_16x16x32_bf16 v[56:59], v[136:139], v[180:183], v[56:59]
	v_mfma_f32_16x16x32_bf16 v[48:51], v[128:131], v[188:191], v[48:51]
	v_mfma_f32_16x16x32_bf16 v[40:43], v[136:139], v[188:191], v[40:43]
	v_mfma_f32_16x16x32_bf16 v[32:35], v[128:131], v[196:199], v[32:35]
	v_mfma_f32_16x16x32_bf16 v[24:27], v[136:139], v[196:199], v[24:27]
	v_mfma_f32_16x16x32_bf16 v[16:19], v[128:131], v[206:209], v[16:19]
	v_mfma_f32_16x16x32_bf16 v[8:11], v[136:139], v[206:209], v[8:11]
	v_mfma_f32_16x16x32_bf16 v[60:63], v[132:135], v[184:187], v[60:63]
	v_mfma_f32_16x16x32_bf16 v[56:59], v[140:143], v[184:187], v[56:59]
	v_mfma_f32_16x16x32_bf16 v[48:51], v[132:135], v[192:195], v[48:51]
	v_mfma_f32_16x16x32_bf16 v[40:43], v[140:143], v[192:195], v[40:43]
	v_mfma_f32_16x16x32_bf16 v[32:35], v[132:135], v[200:203], v[32:35]
	v_mfma_f32_16x16x32_bf16 v[24:27], v[140:143], v[200:203], v[24:27]
	v_mfma_f32_16x16x32_bf16 v[16:19], v[132:135], v[210:213], v[16:19]
	v_mfma_f32_16x16x32_bf16 v[8:11], v[140:143], v[210:213], v[8:11]
	v_mfma_f32_16x16x32_bf16 v[52:55], v[164:167], v[180:183], v[52:55]
	v_mfma_f32_16x16x32_bf16 v[44:47], v[172:175], v[180:183], v[44:47]
	v_mfma_f32_16x16x32_bf16 v[36:39], v[164:167], v[188:191], v[36:39]
	v_mfma_f32_16x16x32_bf16 v[28:31], v[172:175], v[188:191], v[28:31]
	v_mfma_f32_16x16x32_bf16 v[20:23], v[164:167], v[196:199], v[20:23]
	v_mfma_f32_16x16x32_bf16 v[12:15], v[172:175], v[196:199], v[12:15]
	v_mfma_f32_16x16x32_bf16 v[4:7], v[164:167], v[206:209], v[4:7]
	v_mfma_f32_16x16x32_bf16 v[0:3], v[172:175], v[206:209], v[0:3]
	v_mfma_f32_16x16x32_bf16 v[52:55], v[168:171], v[184:187], v[52:55]
	v_mfma_f32_16x16x32_bf16 v[44:47], v[176:179], v[184:187], v[44:47]
	v_mfma_f32_16x16x32_bf16 v[36:39], v[168:171], v[192:195], v[36:39]
	v_mfma_f32_16x16x32_bf16 v[28:31], v[176:179], v[192:195], v[28:31]
	v_mfma_f32_16x16x32_bf16 v[20:23], v[168:171], v[200:203], v[20:23]
	v_mfma_f32_16x16x32_bf16 v[12:15], v[176:179], v[200:203], v[12:15]
	v_mfma_f32_16x16x32_bf16 v[4:7], v[168:171], v[210:213], v[4:7]
	v_mfma_f32_16x16x32_bf16 v[0:3], v[176:179], v[210:213], v[0:3]
	s_barrier
	s_setprio 0
	s_add_i32 s3, 0, 0x18000
	s_add_i32 s33, 0, 0x1c000
	v_add_u32_e32 v140, s3, v159
	v_add_u32_e32 v176, s33, v159
	ds_read_b128 v[128:131], v140
	ds_read_b128 v[132:135], v140 offset:1024
	ds_read_b128 v[136:139], v140 offset:2048
	ds_read_b128 v[140:143], v140 offset:3072
	ds_read_b128 v[164:167], v176
	ds_read_b128 v[168:171], v176 offset:1024
	ds_read_b128 v[172:175], v176 offset:2048
	ds_read_b128 v[176:179], v176 offset:3072
	s_add_u32 s16, s74, 0x80000
	s_addc_u32 s17, s75, 0
	s_mov_b32 m0, s80
	v_lshl_add_u64 v[220:221], s[16:17], 0, v[150:151]
	ds_read_b128 v[180:183], v163 offset:32768
	ds_read_b128 v[184:187], v163 offset:33792
	ds_read_b128 v[188:191], v163 offset:34816
	ds_read_b128 v[192:195], v163 offset:35840
	ds_read_b128 v[196:199], v163 offset:36864
	ds_read_b128 v[200:203], v163 offset:37888
	ds_read_b128 v[206:209], v163 offset:38912
	ds_read_b128 v[210:213], v163 offset:39936
	global_load_lds_dwordx4 v[220:221], off
	v_lshl_add_u64 v[220:221], s[16:17], 0, v[146:147]
	s_mov_b32 m0, s81
	s_nop 0
	global_load_lds_dwordx4 v[220:221], off
	s_waitcnt vmcnt(8)
	s_waitcnt lgkmcnt(0)
	s_setprio 1
	s_barrier
	v_mfma_f32_16x16x32_bf16 v[124:127], v[128:131], v[180:183], v[124:127]
	v_mfma_f32_16x16x32_bf16 v[120:123], v[136:139], v[180:183], v[120:123]
	v_mfma_f32_16x16x32_bf16 v[116:119], v[128:131], v[188:191], v[116:119]
	v_mfma_f32_16x16x32_bf16 v[112:115], v[136:139], v[188:191], v[112:115]
	v_mfma_f32_16x16x32_bf16 v[108:111], v[128:131], v[196:199], v[108:111]
	v_mfma_f32_16x16x32_bf16 v[100:103], v[136:139], v[196:199], v[100:103]
	v_mfma_f32_16x16x32_bf16 v[76:79], v[128:131], v[206:209], v[76:79]
	v_mfma_f32_16x16x32_bf16 v[72:75], v[136:139], v[206:209], v[72:75]
	v_mfma_f32_16x16x32_bf16 v[124:127], v[132:135], v[184:187], v[124:127]
	v_mfma_f32_16x16x32_bf16 v[120:123], v[140:143], v[184:187], v[120:123]
	v_mfma_f32_16x16x32_bf16 v[116:119], v[132:135], v[192:195], v[116:119]
	v_mfma_f32_16x16x32_bf16 v[112:115], v[140:143], v[192:195], v[112:115]
	v_mfma_f32_16x16x32_bf16 v[108:111], v[132:135], v[200:203], v[108:111]
	v_mfma_f32_16x16x32_bf16 v[100:103], v[140:143], v[200:203], v[100:103]
	v_mfma_f32_16x16x32_bf16 v[76:79], v[132:135], v[210:213], v[76:79]
	v_mfma_f32_16x16x32_bf16 v[72:75], v[140:143], v[210:213], v[72:75]
	v_mfma_f32_16x16x32_bf16 v[104:107], v[164:167], v[180:183], v[104:107]
	v_mfma_f32_16x16x32_bf16 v[96:99], v[172:175], v[180:183], v[96:99]
	v_mfma_f32_16x16x32_bf16 v[92:95], v[164:167], v[188:191], v[92:95]
	v_mfma_f32_16x16x32_bf16 v[88:91], v[172:175], v[188:191], v[88:91]
	v_mfma_f32_16x16x32_bf16 v[84:87], v[164:167], v[196:199], v[84:87]
	v_mfma_f32_16x16x32_bf16 v[80:83], v[172:175], v[196:199], v[80:83]
	v_mfma_f32_16x16x32_bf16 v[68:71], v[164:167], v[206:209], v[68:71]
	v_mfma_f32_16x16x32_bf16 v[64:67], v[172:175], v[206:209], v[64:67]
	v_mfma_f32_16x16x32_bf16 v[104:107], v[168:171], v[184:187], v[104:107]
	v_mfma_f32_16x16x32_bf16 v[96:99], v[176:179], v[184:187], v[96:99]
	v_mfma_f32_16x16x32_bf16 v[92:95], v[168:171], v[192:195], v[92:95]
	v_mfma_f32_16x16x32_bf16 v[88:91], v[176:179], v[192:195], v[88:91]
	v_mfma_f32_16x16x32_bf16 v[84:87], v[168:171], v[200:203], v[84:87]
	v_mfma_f32_16x16x32_bf16 v[80:83], v[176:179], v[200:203], v[80:83]
	v_mfma_f32_16x16x32_bf16 v[68:71], v[168:171], v[210:213], v[68:71]
	v_mfma_f32_16x16x32_bf16 v[64:67], v[176:179], v[210:213], v[64:67]
	s_barrier
	s_setprio 0
	s_add_i32 s3, s3, s19
	v_lshl_add_u64 v[156:157], v[156:157], 0, s[44:45]
	s_mov_b32 m0, s3
	ds_read_b128 v[180:183], v163 offset:49152
	ds_read_b128 v[184:187], v163 offset:50176
	ds_read_b128 v[188:191], v163 offset:51200
	ds_read_b128 v[192:195], v163 offset:52224
	ds_read_b128 v[196:199], v163 offset:53248
	ds_read_b128 v[200:203], v163 offset:54272
	ds_read_b128 v[206:209], v163 offset:55296
	ds_read_b128 v[210:213], v163 offset:56320
	global_load_lds_dwordx4 v[156:157], off
	s_add_i32 m0, s3, 0x2000
	s_add_u32 s16, s72, 0x20800
	v_lshl_add_u64 v[156:157], v[214:215], 0, s[44:45]
	s_addc_u32 s17, s73, 0
	s_add_i32 s3, s33, s19
	global_load_lds_dwordx4 v[156:157], off
	v_lshl_add_u64 v[156:157], s[16:17], 0, v[148:149]
	s_mov_b32 m0, s3
	s_nop 0
	global_load_lds_dwordx4 v[156:157], off
	v_lshl_add_u64 v[156:157], s[16:17], 0, v[144:145]
	s_add_i32 m0, s3, 0x2000
	s_nop 0
	global_load_lds_dwordx4 v[156:157], off
	v_lshl_add_u64 v[156:157], v[216:217], 0, s[46:47]
	s_mov_b32 m0, s83
	s_nop 0
	global_load_lds_dwordx4 v[156:157], off
	v_lshl_add_u64 v[156:157], v[218:219], 0, s[46:47]
	s_mov_b32 m0, s84
	s_nop 0
	global_load_lds_dwordx4 v[156:157], off
	s_waitcnt vmcnt(8)
	s_waitcnt lgkmcnt(0)
	s_setprio 1
	s_barrier
	v_mfma_f32_16x16x32_bf16 v[60:63], v[128:131], v[180:183], v[60:63]
	v_mfma_f32_16x16x32_bf16 v[56:59], v[136:139], v[180:183], v[56:59]
	v_mfma_f32_16x16x32_bf16 v[48:51], v[128:131], v[188:191], v[48:51]
	v_mfma_f32_16x16x32_bf16 v[40:43], v[136:139], v[188:191], v[40:43]
	v_mfma_f32_16x16x32_bf16 v[32:35], v[128:131], v[196:199], v[32:35]
	v_mfma_f32_16x16x32_bf16 v[24:27], v[136:139], v[196:199], v[24:27]
	v_mfma_f32_16x16x32_bf16 v[16:19], v[128:131], v[206:209], v[16:19]
	v_mfma_f32_16x16x32_bf16 v[8:11], v[136:139], v[206:209], v[8:11]
	v_mfma_f32_16x16x32_bf16 v[60:63], v[132:135], v[184:187], v[60:63]
	v_mfma_f32_16x16x32_bf16 v[56:59], v[140:143], v[184:187], v[56:59]
	v_mfma_f32_16x16x32_bf16 v[48:51], v[132:135], v[192:195], v[48:51]
	v_mfma_f32_16x16x32_bf16 v[40:43], v[140:143], v[192:195], v[40:43]
	v_mfma_f32_16x16x32_bf16 v[32:35], v[132:135], v[200:203], v[32:35]
	v_mfma_f32_16x16x32_bf16 v[24:27], v[140:143], v[200:203], v[24:27]
	v_mfma_f32_16x16x32_bf16 v[16:19], v[132:135], v[210:213], v[16:19]
	v_mfma_f32_16x16x32_bf16 v[8:11], v[140:143], v[210:213], v[8:11]
	v_mfma_f32_16x16x32_bf16 v[52:55], v[164:167], v[180:183], v[52:55]
	v_mfma_f32_16x16x32_bf16 v[44:47], v[172:175], v[180:183], v[44:47]
	v_mfma_f32_16x16x32_bf16 v[36:39], v[164:167], v[188:191], v[36:39]
	v_mfma_f32_16x16x32_bf16 v[28:31], v[172:175], v[188:191], v[28:31]
	v_mfma_f32_16x16x32_bf16 v[20:23], v[164:167], v[196:199], v[20:23]
	v_mfma_f32_16x16x32_bf16 v[12:15], v[172:175], v[196:199], v[12:15]
	v_mfma_f32_16x16x32_bf16 v[4:7], v[164:167], v[206:209], v[4:7]
	v_mfma_f32_16x16x32_bf16 v[0:3], v[172:175], v[206:209], v[0:3]
	v_mfma_f32_16x16x32_bf16 v[52:55], v[168:171], v[184:187], v[52:55]
	v_mfma_f32_16x16x32_bf16 v[44:47], v[176:179], v[184:187], v[44:47]
	v_mfma_f32_16x16x32_bf16 v[36:39], v[168:171], v[192:195], v[36:39]
	v_mfma_f32_16x16x32_bf16 v[28:31], v[176:179], v[192:195], v[28:31]
	v_mfma_f32_16x16x32_bf16 v[20:23], v[168:171], v[200:203], v[20:23]
	v_mfma_f32_16x16x32_bf16 v[12:15], v[176:179], v[200:203], v[12:15]
	v_mfma_f32_16x16x32_bf16 v[4:7], v[168:171], v[210:213], v[4:7]
	v_mfma_f32_16x16x32_bf16 v[0:3], v[176:179], v[210:213], v[0:3]
	s_barrier
	s_setprio 0
	s_add_i32 vcc_hi, vcc_hi, 2
	s_add_u32 s97, s97, 0x1000
	s_addc_u32 vcc_lo, vcc_lo, 0
	s_add_u32 s70, s70, 0x100
	s_addc_u32 s71, s71, 0
	s_cmp_gt_u32 vcc_hi, 5
	s_cbranch_scc0 .LBB0_432
	s_and_b64 vcc, exec, s[48:49]
	s_cbranch_vccz .LBB0_435
	s_barrier

.LBB0_513:
	ds_read_b128 v[128:131], v230
	ds_read_b128 v[132:135], v230 offset:1024
	ds_read_b128 v[136:139], v230 offset:2048
	ds_read_b128 v[140:143], v230 offset:3072
	ds_read_b128 v[144:147], v231
	ds_read_b128 v[148:151], v231 offset:1024
	ds_read_b128 v[152:155], v231 offset:2048
	ds_read_b128 v[156:159], v231 offset:3072
	s_add_u32 s3, s56, 0xfff00080
	s_addc_u32 s16, s57, -1
	s_cmp_eq_u32 s82, 60
	s_cselect_b32 s61, s43, s16
	s_cselect_b32 s60, s49, s3
	s_cselect_b32 s59, s41, s81
	s_cselect_b32 s58, s55, s80
	v_lshl_add_u64 v[214:215], s[56:57], 0, v[196:197]
	s_add_i32 m0, s62, 0xc000
	ds_read_b128 v[160:163], v232
	ds_read_b128 v[164:167], v232 offset:1024
	ds_read_b128 v[168:171], v232 offset:2048
	ds_read_b128 v[172:175], v232 offset:3072
	ds_read_b128 v[176:179], v232 offset:4096
	ds_read_b128 v[180:183], v232 offset:5120
	ds_read_b128 v[206:209], v232 offset:6144
	ds_read_b128 v[210:213], v232 offset:7168
	global_load_lds_dwordx4 v[214:215], off
	v_lshl_add_u64 v[214:215], s[56:57], 0, v[198:199]
	s_add_i32 m0, s62, 0xe000
	s_nop 0
	global_load_lds_dwordx4 v[214:215], off
	s_waitcnt vmcnt(8)
	s_waitcnt lgkmcnt(0)
	s_setprio 1
	s_barrier
	v_mfma_f32_16x16x32_bf16 v[124:127], v[128:131], v[160:163], v[124:127]
	v_mfma_f32_16x16x32_bf16 v[120:123], v[136:139], v[160:163], v[120:123]
	v_mfma_f32_16x16x32_bf16 v[108:111], v[128:131], v[168:171], v[108:111]
	v_mfma_f32_16x16x32_bf16 v[104:107], v[136:139], v[168:171], v[104:107]
	v_mfma_f32_16x16x32_bf16 v[92:95], v[128:131], v[176:179], v[92:95]
	v_mfma_f32_16x16x32_bf16 v[88:91], v[136:139], v[176:179], v[88:91]
	v_mfma_f32_16x16x32_bf16 v[76:79], v[128:131], v[206:209], v[76:79]
	v_mfma_f32_16x16x32_bf16 v[72:75], v[136:139], v[206:209], v[72:75]
	v_mfma_f32_16x16x32_bf16 v[124:127], v[132:135], v[164:167], v[124:127]
	v_mfma_f32_16x16x32_bf16 v[120:123], v[140:143], v[164:167], v[120:123]
	v_mfma_f32_16x16x32_bf16 v[108:111], v[132:135], v[172:175], v[108:111]
	v_mfma_f32_16x16x32_bf16 v[104:107], v[140:143], v[172:175], v[104:107]
	v_mfma_f32_16x16x32_bf16 v[92:95], v[132:135], v[180:183], v[92:95]
	v_mfma_f32_16x16x32_bf16 v[88:91], v[140:143], v[180:183], v[88:91]
	v_mfma_f32_16x16x32_bf16 v[76:79], v[132:135], v[210:213], v[76:79]
	v_mfma_f32_16x16x32_bf16 v[72:75], v[140:143], v[210:213], v[72:75]
	v_mfma_f32_16x16x32_bf16 v[116:119], v[144:147], v[160:163], v[116:119]
	v_mfma_f32_16x16x32_bf16 v[112:115], v[152:155], v[160:163], v[112:115]
	v_mfma_f32_16x16x32_bf16 v[100:103], v[144:147], v[168:171], v[100:103]
	v_mfma_f32_16x16x32_bf16 v[96:99], v[152:155], v[168:171], v[96:99]
	v_mfma_f32_16x16x32_bf16 v[84:87], v[144:147], v[176:179], v[84:87]
	v_mfma_f32_16x16x32_bf16 v[80:83], v[152:155], v[176:179], v[80:83]
	v_mfma_f32_16x16x32_bf16 v[68:71], v[144:147], v[206:209], v[68:71]
	v_mfma_f32_16x16x32_bf16 v[64:67], v[152:155], v[206:209], v[64:67]
	v_mfma_f32_16x16x32_bf16 v[116:119], v[148:151], v[164:167], v[116:119]
	v_mfma_f32_16x16x32_bf16 v[112:115], v[156:159], v[164:167], v[112:115]
	v_mfma_f32_16x16x32_bf16 v[100:103], v[148:151], v[172:175], v[100:103]
	v_mfma_f32_16x16x32_bf16 v[96:99], v[156:159], v[172:175], v[96:99]
	v_mfma_f32_16x16x32_bf16 v[84:87], v[148:151], v[180:183], v[84:87]
	v_mfma_f32_16x16x32_bf16 v[80:83], v[156:159], v[180:183], v[80:83]
	v_mfma_f32_16x16x32_bf16 v[68:71], v[148:151], v[210:213], v[68:71]
	v_mfma_f32_16x16x32_bf16 v[64:67], v[156:159], v[210:213], v[64:67]
	s_barrier
	s_setprio 0
	s_add_i32 s3, s75, s19
	v_lshl_add_u64 v[214:215], s[58:59], 0, v[186:187]
	s_mov_b32 m0, s3
	ds_read_b128 v[160:163], v232 offset:16384
	ds_read_b128 v[164:167], v232 offset:17408
	ds_read_b128 v[168:171], v232 offset:18432
	ds_read_b128 v[172:175], v232 offset:19456
	ds_read_b128 v[176:179], v232 offset:20480
	ds_read_b128 v[180:183], v232 offset:21504
	ds_read_b128 v[206:209], v232 offset:22528
	ds_read_b128 v[210:213], v232 offset:23552
	global_load_lds_dwordx4 v[214:215], off
	s_add_i32 m0, s3, 0x2000
	s_add_u32 s16, s58, 0x100000
	v_lshl_add_u64 v[216:217], s[58:59], 0, v[190:191]
	s_addc_u32 s17, s59, 0
	s_add_i32 s3, s76, s19
	global_load_lds_dwordx4 v[216:217], off
	v_lshl_add_u64 v[218:219], s[16:17], 0, v[186:187]
	s_mov_b32 m0, s3
	v_lshl_add_u64 v[220:221], s[60:61], 0, v[188:189]
	global_load_lds_dwordx4 v[218:219], off
	v_lshl_add_u64 v[218:219], s[16:17], 0, v[190:191]
	s_add_i32 m0, s3, 0x2000
	s_nop 0
	global_load_lds_dwordx4 v[218:219], off
	v_lshl_add_u64 v[218:219], s[60:61], 0, v[184:185]
	s_mov_b32 m0, s62
	s_nop 0
	global_load_lds_dwordx4 v[218:219], off
	s_mov_b32 m0, s63
	s_nop 0
	global_load_lds_dwordx4 v[220:221], off
	s_waitcnt vmcnt(8)
	s_waitcnt lgkmcnt(0)
	s_setprio 1
	s_barrier
	v_mfma_f32_16x16x32_bf16 v[60:63], v[128:131], v[160:163], v[60:63]
	v_mfma_f32_16x16x32_bf16 v[56:59], v[136:139], v[160:163], v[56:59]
	v_mfma_f32_16x16x32_bf16 v[44:47], v[128:131], v[168:171], v[44:47]
	v_mfma_f32_16x16x32_bf16 v[40:43], v[136:139], v[168:171], v[40:43]
	v_mfma_f32_16x16x32_bf16 v[28:31], v[128:131], v[176:179], v[28:31]
	v_mfma_f32_16x16x32_bf16 v[24:27], v[136:139], v[176:179], v[24:27]
	v_mfma_f32_16x16x32_bf16 v[12:15], v[128:131], v[206:209], v[12:15]
	v_mfma_f32_16x16x32_bf16 v[8:11], v[136:139], v[206:209], v[8:11]
	v_mfma_f32_16x16x32_bf16 v[60:63], v[132:135], v[164:167], v[60:63]
	v_mfma_f32_16x16x32_bf16 v[56:59], v[140:143], v[164:167], v[56:59]
	v_mfma_f32_16x16x32_bf16 v[44:47], v[132:135], v[172:175], v[44:47]
	v_mfma_f32_16x16x32_bf16 v[40:43], v[140:143], v[172:175], v[40:43]
	v_mfma_f32_16x16x32_bf16 v[28:31], v[132:135], v[180:183], v[28:31]
	v_mfma_f32_16x16x32_bf16 v[24:27], v[140:143], v[180:183], v[24:27]
	v_mfma_f32_16x16x32_bf16 v[12:15], v[132:135], v[210:213], v[12:15]
	v_mfma_f32_16x16x32_bf16 v[8:11], v[140:143], v[210:213], v[8:11]
	v_mfma_f32_16x16x32_bf16 v[52:55], v[144:147], v[160:163], v[52:55]
	v_mfma_f32_16x16x32_bf16 v[48:51], v[152:155], v[160:163], v[48:51]
	v_mfma_f32_16x16x32_bf16 v[36:39], v[144:147], v[168:171], v[36:39]
	v_mfma_f32_16x16x32_bf16 v[32:35], v[152:155], v[168:171], v[32:35]
	v_mfma_f32_16x16x32_bf16 v[20:23], v[144:147], v[176:179], v[20:23]
	v_mfma_f32_16x16x32_bf16 v[16:19], v[152:155], v[176:179], v[16:19]
	v_mfma_f32_16x16x32_bf16 v[4:7], v[144:147], v[206:209], v[4:7]
	v_mfma_f32_16x16x32_bf16 v[0:3], v[152:155], v[206:209], v[0:3]
	v_mfma_f32_16x16x32_bf16 v[52:55], v[148:151], v[164:167], v[52:55]
	v_mfma_f32_16x16x32_bf16 v[48:51], v[156:159], v[164:167], v[48:51]
	v_mfma_f32_16x16x32_bf16 v[36:39], v[148:151], v[172:175], v[36:39]
	v_mfma_f32_16x16x32_bf16 v[32:35], v[156:159], v[172:175], v[32:35]
	v_mfma_f32_16x16x32_bf16 v[20:23], v[148:151], v[180:183], v[20:23]
	v_mfma_f32_16x16x32_bf16 v[16:19], v[156:159], v[180:183], v[16:19]
	v_mfma_f32_16x16x32_bf16 v[4:7], v[148:151], v[210:213], v[4:7]
	v_mfma_f32_16x16x32_bf16 v[0:3], v[156:159], v[210:213], v[0:3]
	s_barrier
	s_setprio 0
	s_add_i32 s3, 0, 0x18000
	s_add_i32 s33, 0, 0x1c000
	v_add_u32_e32 v140, s3, v229
	v_add_u32_e32 v156, s33, v229
	ds_read_b128 v[128:131], v140
	ds_read_b128 v[132:135], v140 offset:1024
	ds_read_b128 v[136:139], v140 offset:2048
	ds_read_b128 v[140:143], v140 offset:3072
	ds_read_b128 v[144:147], v156
	ds_read_b128 v[148:151], v156 offset:1024
	ds_read_b128 v[152:155], v156 offset:2048
	ds_read_b128 v[156:159], v156 offset:3072
	s_add_u32 s16, s60, 0x100000
	s_addc_u32 s17, s61, 0
	s_mov_b32 m0, s64
	v_lshl_add_u64 v[222:223], s[16:17], 0, v[184:185]
	ds_read_b128 v[160:163], v232 offset:32768
	ds_read_b128 v[164:167], v232 offset:33792
	ds_read_b128 v[168:171], v232 offset:34816
	ds_read_b128 v[172:175], v232 offset:35840
	ds_read_b128 v[176:179], v232 offset:36864
	ds_read_b128 v[180:183], v232 offset:37888
	ds_read_b128 v[206:209], v232 offset:38912
	ds_read_b128 v[210:213], v232 offset:39936
	global_load_lds_dwordx4 v[222:223], off
	v_lshl_add_u64 v[222:223], s[16:17], 0, v[188:189]
	s_mov_b32 m0, s65
	s_nop 0
	global_load_lds_dwordx4 v[222:223], off
	s_waitcnt vmcnt(8)
	s_waitcnt lgkmcnt(0)
	s_setprio 1
	s_barrier
	v_mfma_f32_16x16x32_bf16 v[124:127], v[128:131], v[160:163], v[124:127]
	v_mfma_f32_16x16x32_bf16 v[120:123], v[136:139], v[160:163], v[120:123]
	v_mfma_f32_16x16x32_bf16 v[108:111], v[128:131], v[168:171], v[108:111]
	v_mfma_f32_16x16x32_bf16 v[104:107], v[136:139], v[168:171], v[104:107]
	v_mfma_f32_16x16x32_bf16 v[92:95], v[128:131], v[176:179], v[92:95]
	v_mfma_f32_16x16x32_bf16 v[88:91], v[136:139], v[176:179], v[88:91]
	v_mfma_f32_16x16x32_bf16 v[76:79], v[128:131], v[206:209], v[76:79]
	v_mfma_f32_16x16x32_bf16 v[72:75], v[136:139], v[206:209], v[72:75]
	v_mfma_f32_16x16x32_bf16 v[124:127], v[132:135], v[164:167], v[124:127]
	v_mfma_f32_16x16x32_bf16 v[120:123], v[140:143], v[164:167], v[120:123]
	v_mfma_f32_16x16x32_bf16 v[108:111], v[132:135], v[172:175], v[108:111]
	v_mfma_f32_16x16x32_bf16 v[104:107], v[140:143], v[172:175], v[104:107]
	v_mfma_f32_16x16x32_bf16 v[92:95], v[132:135], v[180:183], v[92:95]
	v_mfma_f32_16x16x32_bf16 v[88:91], v[140:143], v[180:183], v[88:91]
	v_mfma_f32_16x16x32_bf16 v[76:79], v[132:135], v[210:213], v[76:79]
	v_mfma_f32_16x16x32_bf16 v[72:75], v[140:143], v[210:213], v[72:75]
	v_mfma_f32_16x16x32_bf16 v[116:119], v[144:147], v[160:163], v[116:119]
	v_mfma_f32_16x16x32_bf16 v[112:115], v[152:155], v[160:163], v[112:115]
	v_mfma_f32_16x16x32_bf16 v[100:103], v[144:147], v[168:171], v[100:103]
	v_mfma_f32_16x16x32_bf16 v[96:99], v[152:155], v[168:171], v[96:99]
	v_mfma_f32_16x16x32_bf16 v[84:87], v[144:147], v[176:179], v[84:87]
	v_mfma_f32_16x16x32_bf16 v[80:83], v[152:155], v[176:179], v[80:83]
	v_mfma_f32_16x16x32_bf16 v[68:71], v[144:147], v[206:209], v[68:71]
	v_mfma_f32_16x16x32_bf16 v[64:67], v[152:155], v[206:209], v[64:67]
	v_mfma_f32_16x16x32_bf16 v[116:119], v[148:151], v[164:167], v[116:119]
	v_mfma_f32_16x16x32_bf16 v[112:115], v[156:159], v[164:167], v[112:115]
	v_mfma_f32_16x16x32_bf16 v[100:103], v[148:151], v[172:175], v[100:103]
	v_mfma_f32_16x16x32_bf16 v[96:99], v[156:159], v[172:175], v[96:99]
	v_mfma_f32_16x16x32_bf16 v[84:87], v[148:151], v[180:183], v[84:87]
	v_mfma_f32_16x16x32_bf16 v[80:83], v[156:159], v[180:183], v[80:83]
	v_mfma_f32_16x16x32_bf16 v[68:71], v[148:151], v[210:213], v[68:71]
	v_mfma_f32_16x16x32_bf16 v[64:67], v[156:159], v[210:213], v[64:67]
	s_barrier
	s_setprio 0
	s_add_i32 s3, s3, s19
	v_lshl_add_u64 v[214:215], v[214:215], 0, s[14:15]
	s_mov_b32 m0, s3
	ds_read_b128 v[160:163], v232 offset:49152
	ds_read_b128 v[164:167], v232 offset:50176
	ds_read_b128 v[168:171], v232 offset:51200
	ds_read_b128 v[172:175], v232 offset:52224
	ds_read_b128 v[176:179], v232 offset:53248
	ds_read_b128 v[180:183], v232 offset:54272
	ds_read_b128 v[206:209], v232 offset:55296
	ds_read_b128 v[210:213], v232 offset:56320
	global_load_lds_dwordx4 v[214:215], off
	s_add_i32 m0, s3, 0x2000
	s_add_u32 s16, s58, 0x100800
	v_lshl_add_u64 v[214:215], v[216:217], 0, s[14:15]
	s_addc_u32 s17, s59, 0
	s_add_i32 s3, s33, s19
	global_load_lds_dwordx4 v[214:215], off
	v_lshl_add_u64 v[214:215], s[16:17], 0, v[186:187]
	s_mov_b32 m0, s3
	s_nop 0
	global_load_lds_dwordx4 v[214:215], off
	v_lshl_add_u64 v[214:215], s[16:17], 0, v[190:191]
	s_add_i32 m0, s3, 0x2000
	s_nop 0
	global_load_lds_dwordx4 v[214:215], off
	v_lshl_add_u64 v[214:215], v[218:219], 0, s[36:37]
	s_mov_b32 m0, s70
	s_nop 0
	global_load_lds_dwordx4 v[214:215], off
	v_lshl_add_u64 v[214:215], v[220:221], 0, s[36:37]
	s_mov_b32 m0, s71
	s_nop 0
	global_load_lds_dwordx4 v[214:215], off
	s_waitcnt vmcnt(8)
	s_waitcnt lgkmcnt(0)
	s_setprio 1
	s_barrier
	v_mfma_f32_16x16x32_bf16 v[60:63], v[128:131], v[160:163], v[60:63]
	v_mfma_f32_16x16x32_bf16 v[56:59], v[136:139], v[160:163], v[56:59]
	v_mfma_f32_16x16x32_bf16 v[44:47], v[128:131], v[168:171], v[44:47]
	v_mfma_f32_16x16x32_bf16 v[40:43], v[136:139], v[168:171], v[40:43]
	v_mfma_f32_16x16x32_bf16 v[28:31], v[128:131], v[176:179], v[28:31]
	v_mfma_f32_16x16x32_bf16 v[24:27], v[136:139], v[176:179], v[24:27]
	v_mfma_f32_16x16x32_bf16 v[12:15], v[128:131], v[206:209], v[12:15]
	v_mfma_f32_16x16x32_bf16 v[8:11], v[136:139], v[206:209], v[8:11]
	v_mfma_f32_16x16x32_bf16 v[60:63], v[132:135], v[164:167], v[60:63]
	v_mfma_f32_16x16x32_bf16 v[56:59], v[140:143], v[164:167], v[56:59]
	v_mfma_f32_16x16x32_bf16 v[44:47], v[132:135], v[172:175], v[44:47]
	v_mfma_f32_16x16x32_bf16 v[40:43], v[140:143], v[172:175], v[40:43]
	v_mfma_f32_16x16x32_bf16 v[28:31], v[132:135], v[180:183], v[28:31]
	v_mfma_f32_16x16x32_bf16 v[24:27], v[140:143], v[180:183], v[24:27]
	v_mfma_f32_16x16x32_bf16 v[12:15], v[132:135], v[210:213], v[12:15]
	v_mfma_f32_16x16x32_bf16 v[8:11], v[140:143], v[210:213], v[8:11]
	v_mfma_f32_16x16x32_bf16 v[52:55], v[144:147], v[160:163], v[52:55]
	v_mfma_f32_16x16x32_bf16 v[48:51], v[152:155], v[160:163], v[48:51]
	v_mfma_f32_16x16x32_bf16 v[36:39], v[144:147], v[168:171], v[36:39]
	v_mfma_f32_16x16x32_bf16 v[32:35], v[152:155], v[168:171], v[32:35]
	v_mfma_f32_16x16x32_bf16 v[20:23], v[144:147], v[176:179], v[20:23]
	v_mfma_f32_16x16x32_bf16 v[16:19], v[152:155], v[176:179], v[16:19]
	v_mfma_f32_16x16x32_bf16 v[4:7], v[144:147], v[206:209], v[4:7]
	v_mfma_f32_16x16x32_bf16 v[0:3], v[152:155], v[206:209], v[0:3]
	v_mfma_f32_16x16x32_bf16 v[52:55], v[148:151], v[164:167], v[52:55]
	v_mfma_f32_16x16x32_bf16 v[48:51], v[156:159], v[164:167], v[48:51]
	v_mfma_f32_16x16x32_bf16 v[36:39], v[148:151], v[172:175], v[36:39]
	v_mfma_f32_16x16x32_bf16 v[32:35], v[156:159], v[172:175], v[32:35]
	v_mfma_f32_16x16x32_bf16 v[20:23], v[148:151], v[180:183], v[20:23]
	v_mfma_f32_16x16x32_bf16 v[16:19], v[156:159], v[180:183], v[16:19]
	v_mfma_f32_16x16x32_bf16 v[4:7], v[148:151], v[210:213], v[4:7]
	v_mfma_f32_16x16x32_bf16 v[0:3], v[156:159], v[210:213], v[0:3]
	s_barrier
	s_setprio 0
	s_add_i32 s82, s82, 2
	s_add_u32 s80, s80, 0x1000
	s_addc_u32 s81, s81, 0
	s_add_u32 s56, s56, 0x100
	s_addc_u32 s57, s57, 0
	s_cmp_gt_u32 s82, 61
	s_cbranch_scc0 .LBB0_513
	s_and_b64 vcc, exec, s[38:39]
	s_cbranch_vccz .LBB0_516
	s_barrier

.LBB0_639:
	ds_read_b128 v[52:55], v188
	ds_read_b128 v[56:59], v188 offset:1024
	ds_read_b128 v[60:63], v188 offset:2048
	ds_read_b128 v[64:67], v188 offset:3072
	ds_read_b128 v[72:75], v189
	ds_read_b128 v[76:79], v189 offset:1024
	ds_read_b128 v[80:83], v189 offset:2048
	ds_read_b128 v[84:87], v189 offset:3072
	s_add_u32 s60, s14, 0x1000
	s_addc_u32 s61, s15, 0
	s_cmp_eq_u32 s93, 60
	s_cselect_b32 s65, s11, s61
	s_cselect_b32 s64, s13, s60
	s_cselect_b32 s63, s53, s91
	s_cselect_b32 s62, s55, s90
	v_lshl_add_u64 v[224:225], s[14:15], 0, v[172:173]
	s_add_i32 m0, s66, 0xc000
	ds_read_b128 v[180:183], v190
	ds_read_b128 v[196:199], v190 offset:1024
	ds_read_b128 v[200:203], v190 offset:2048
	ds_read_b128 v[204:207], v190 offset:3072
	ds_read_b128 v[208:211], v190 offset:4096
	ds_read_b128 v[212:215], v190 offset:5120
	ds_read_b128 v[216:219], v190 offset:6144
	ds_read_b128 v[220:223], v190 offset:7168
	global_load_lds_dwordx4 v[224:225], off
	v_lshl_add_u64 v[224:225], s[14:15], 0, v[174:175]
	s_add_i32 m0, s66, 0xe000
	s_nop 0
	global_load_lds_dwordx4 v[224:225], off
	s_waitcnt vmcnt(8)
	s_waitcnt lgkmcnt(0)
	s_setprio 1
	s_barrier
	v_mfma_f32_16x16x32_bf16 v[156:159], v[52:55], v[180:183], v[156:159]
	v_mfma_f32_16x16x32_bf16 v[152:155], v[60:63], v[180:183], v[152:155]
	v_mfma_f32_16x16x32_bf16 v[140:143], v[52:55], v[200:203], v[140:143]
	v_mfma_f32_16x16x32_bf16 v[136:139], v[60:63], v[200:203], v[136:139]
	v_mfma_f32_16x16x32_bf16 v[124:127], v[52:55], v[208:211], v[124:127]
	v_mfma_f32_16x16x32_bf16 v[120:123], v[60:63], v[208:211], v[120:123]
	v_mfma_f32_16x16x32_bf16 v[108:111], v[52:55], v[216:219], v[108:111]
	v_mfma_f32_16x16x32_bf16 v[104:107], v[60:63], v[216:219], v[104:107]
	v_mfma_f32_16x16x32_bf16 v[156:159], v[56:59], v[196:199], v[156:159]
	v_mfma_f32_16x16x32_bf16 v[152:155], v[64:67], v[196:199], v[152:155]
	v_mfma_f32_16x16x32_bf16 v[140:143], v[56:59], v[204:207], v[140:143]
	v_mfma_f32_16x16x32_bf16 v[136:139], v[64:67], v[204:207], v[136:139]
	v_mfma_f32_16x16x32_bf16 v[124:127], v[56:59], v[212:215], v[124:127]
	v_mfma_f32_16x16x32_bf16 v[120:123], v[64:67], v[212:215], v[120:123]
	v_mfma_f32_16x16x32_bf16 v[108:111], v[56:59], v[220:223], v[108:111]
	v_mfma_f32_16x16x32_bf16 v[104:107], v[64:67], v[220:223], v[104:107]
	v_mfma_f32_16x16x32_bf16 v[144:147], v[72:75], v[180:183], v[144:147]
	v_mfma_f32_16x16x32_bf16 v[148:151], v[80:83], v[180:183], v[148:151]
	v_mfma_f32_16x16x32_bf16 v[128:131], v[72:75], v[200:203], v[128:131]
	v_mfma_f32_16x16x32_bf16 v[132:135], v[80:83], v[200:203], v[132:135]
	v_mfma_f32_16x16x32_bf16 v[112:115], v[72:75], v[208:211], v[112:115]
	v_mfma_f32_16x16x32_bf16 v[116:119], v[80:83], v[208:211], v[116:119]
	v_mfma_f32_16x16x32_bf16 v[96:99], v[72:75], v[216:219], v[96:99]
	v_mfma_f32_16x16x32_bf16 v[100:103], v[80:83], v[216:219], v[100:103]
	v_mfma_f32_16x16x32_bf16 v[144:147], v[76:79], v[196:199], v[144:147]
	v_mfma_f32_16x16x32_bf16 v[148:151], v[84:87], v[196:199], v[148:151]
	v_mfma_f32_16x16x32_bf16 v[128:131], v[76:79], v[204:207], v[128:131]
	v_mfma_f32_16x16x32_bf16 v[132:135], v[84:87], v[204:207], v[132:135]
	v_mfma_f32_16x16x32_bf16 v[112:115], v[76:79], v[212:215], v[112:115]
	v_mfma_f32_16x16x32_bf16 v[116:119], v[84:87], v[212:215], v[116:119]
	v_mfma_f32_16x16x32_bf16 v[96:99], v[76:79], v[220:223], v[96:99]
	v_mfma_f32_16x16x32_bf16 v[100:103], v[84:87], v[220:223], v[100:103]
	s_barrier
	s_setprio 0
	s_add_i32 s3, s80, s19
	v_lshl_add_u64 v[224:225], s[62:63], 0, v[162:163]
	s_mov_b32 m0, s3
	ds_read_b128 v[180:183], v190 offset:16384
	ds_read_b128 v[196:199], v190 offset:17408
	ds_read_b128 v[200:203], v190 offset:18432
	ds_read_b128 v[204:207], v190 offset:19456
	ds_read_b128 v[208:211], v190 offset:20480
	ds_read_b128 v[212:215], v190 offset:21504
	ds_read_b128 v[216:219], v190 offset:22528
	ds_read_b128 v[220:223], v190 offset:23552
	global_load_lds_dwordx4 v[224:225], off
	s_add_i32 m0, s3, 0x2000
	s_add_u32 s14, s62, 0x100000
	v_lshl_add_u64 v[228:229], s[62:63], 0, v[166:167]
	s_addc_u32 s15, s63, 0
	s_add_i32 s3, s81, s19
	global_load_lds_dwordx4 v[228:229], off
	v_lshl_add_u64 v[230:231], s[14:15], 0, v[162:163]
	s_mov_b32 m0, s3
	v_lshl_add_u64 v[232:233], s[64:65], 0, v[164:165]
	global_load_lds_dwordx4 v[230:231], off
	v_lshl_add_u64 v[230:231], s[14:15], 0, v[166:167]
	s_add_i32 m0, s3, 0x2000
	s_nop 0
	global_load_lds_dwordx4 v[230:231], off
	v_lshl_add_u64 v[230:231], s[64:65], 0, v[160:161]
	s_mov_b32 m0, s66
	s_nop 0
	global_load_lds_dwordx4 v[230:231], off
	s_mov_b32 m0, s67
	s_nop 0
	global_load_lds_dwordx4 v[232:233], off
	s_waitcnt vmcnt(8)
	s_waitcnt lgkmcnt(0)
	s_setprio 1
	s_barrier
	v_mfma_f32_16x16x32_bf16 v[92:95], v[52:55], v[180:183], v[92:95]
	v_mfma_f32_16x16x32_bf16 v[88:91], v[60:63], v[180:183], v[88:91]
	v_mfma_f32_16x16x32_bf16 v[44:47], v[52:55], v[200:203], v[44:47]
	v_mfma_f32_16x16x32_bf16 v[40:43], v[60:63], v[200:203], v[40:43]
	v_mfma_f32_16x16x32_bf16 v[28:31], v[52:55], v[208:211], v[28:31]
	v_mfma_f32_16x16x32_bf16 v[24:27], v[60:63], v[208:211], v[24:27]
	v_mfma_f32_16x16x32_bf16 v[12:15], v[52:55], v[216:219], v[12:15]
	v_mfma_f32_16x16x32_bf16 v[8:11], v[60:63], v[216:219], v[8:11]
	v_mfma_f32_16x16x32_bf16 v[92:95], v[56:59], v[196:199], v[92:95]
	v_mfma_f32_16x16x32_bf16 v[88:91], v[64:67], v[196:199], v[88:91]
	v_mfma_f32_16x16x32_bf16 v[44:47], v[56:59], v[204:207], v[44:47]
	v_mfma_f32_16x16x32_bf16 v[40:43], v[64:67], v[204:207], v[40:43]
	v_mfma_f32_16x16x32_bf16 v[28:31], v[56:59], v[212:215], v[28:31]
	v_mfma_f32_16x16x32_bf16 v[24:27], v[64:67], v[212:215], v[24:27]
	v_mfma_f32_16x16x32_bf16 v[12:15], v[56:59], v[220:223], v[12:15]
	v_mfma_f32_16x16x32_bf16 v[8:11], v[64:67], v[220:223], v[8:11]
	v_mfma_f32_16x16x32_bf16 v[48:51], v[72:75], v[180:183], v[48:51]
	v_mfma_f32_16x16x32_bf16 v[32:35], v[72:75], v[200:203], v[32:35]
	v_mfma_f32_16x16x32_bf16 v[36:39], v[80:83], v[200:203], v[36:39]
	v_mfma_f32_16x16x32_bf16 v[16:19], v[72:75], v[208:211], v[16:19]
	v_mfma_f32_16x16x32_bf16 v[20:23], v[80:83], v[208:211], v[20:23]
	v_mfma_f32_16x16x32_bf16 v[0:3], v[72:75], v[216:219], v[0:3]
	v_mfma_f32_16x16x32_bf16 v[4:7], v[80:83], v[216:219], v[4:7]
	v_mfma_f32_16x16x32_bf16 v[48:51], v[76:79], v[196:199], v[48:51]
	v_mfma_f32_16x16x32_bf16 v[52:55], v[80:83], v[180:183], v[68:71]
	v_mfma_f32_16x16x32_bf16 v[32:35], v[76:79], v[204:207], v[32:35]
	v_mfma_f32_16x16x32_bf16 v[36:39], v[84:87], v[204:207], v[36:39]
	v_mfma_f32_16x16x32_bf16 v[16:19], v[76:79], v[212:215], v[16:19]
	v_mfma_f32_16x16x32_bf16 v[20:23], v[84:87], v[212:215], v[20:23]
	v_mfma_f32_16x16x32_bf16 v[0:3], v[76:79], v[220:223], v[0:3]
	v_mfma_f32_16x16x32_bf16 v[4:7], v[84:87], v[220:223], v[4:7]
	v_mfma_f32_16x16x32_bf16 v[52:55], v[84:87], v[196:199], v[52:55]
	s_barrier
	s_setprio 0
	s_add_i32 s3, 0, 0x18000
	s_add_i32 s16, 0, 0x1c000
	v_add_u32_e32 v68, s3, v171
	v_add_u32_e32 v84, s16, v171
	ds_read_b128 v[56:59], v68
	ds_read_b128 v[60:63], v68 offset:1024
	ds_read_b128 v[64:67], v68 offset:2048
	ds_read_b128 v[68:71], v68 offset:3072
	ds_read_b128 v[72:75], v84
	ds_read_b128 v[76:79], v84 offset:1024
	ds_read_b128 v[80:83], v84 offset:2048
	ds_read_b128 v[84:87], v84 offset:3072
	s_add_u32 s14, s64, 0x80000
	s_addc_u32 s15, s65, 0
	s_mov_b32 m0, s70
	v_lshl_add_u64 v[234:235], s[14:15], 0, v[160:161]
	ds_read_b128 v[180:183], v190 offset:32768
	ds_read_b128 v[196:199], v190 offset:33792
	ds_read_b128 v[200:203], v190 offset:34816
	ds_read_b128 v[204:207], v190 offset:35840
	ds_read_b128 v[208:211], v190 offset:36864
	ds_read_b128 v[212:215], v190 offset:37888
	ds_read_b128 v[216:219], v190 offset:38912
	ds_read_b128 v[220:223], v190 offset:39936
	global_load_lds_dwordx4 v[234:235], off
	v_lshl_add_u64 v[234:235], s[14:15], 0, v[164:165]
	s_mov_b32 m0, s71
	s_nop 0
	global_load_lds_dwordx4 v[234:235], off
	s_waitcnt vmcnt(8)
	s_waitcnt lgkmcnt(0)
	s_setprio 1
	s_barrier
	v_mfma_f32_16x16x32_bf16 v[156:159], v[56:59], v[180:183], v[156:159]
	v_mfma_f32_16x16x32_bf16 v[152:155], v[64:67], v[180:183], v[152:155]
	v_mfma_f32_16x16x32_bf16 v[140:143], v[56:59], v[200:203], v[140:143]
	v_mfma_f32_16x16x32_bf16 v[136:139], v[64:67], v[200:203], v[136:139]
	v_mfma_f32_16x16x32_bf16 v[124:127], v[56:59], v[208:211], v[124:127]
	v_mfma_f32_16x16x32_bf16 v[120:123], v[64:67], v[208:211], v[120:123]
	v_mfma_f32_16x16x32_bf16 v[108:111], v[56:59], v[216:219], v[108:111]
	v_mfma_f32_16x16x32_bf16 v[104:107], v[64:67], v[216:219], v[104:107]
	v_mfma_f32_16x16x32_bf16 v[156:159], v[60:63], v[196:199], v[156:159]
	v_mfma_f32_16x16x32_bf16 v[152:155], v[68:71], v[196:199], v[152:155]
	v_mfma_f32_16x16x32_bf16 v[140:143], v[60:63], v[204:207], v[140:143]
	v_mfma_f32_16x16x32_bf16 v[136:139], v[68:71], v[204:207], v[136:139]
	v_mfma_f32_16x16x32_bf16 v[124:127], v[60:63], v[212:215], v[124:127]
	v_mfma_f32_16x16x32_bf16 v[120:123], v[68:71], v[212:215], v[120:123]
	v_mfma_f32_16x16x32_bf16 v[108:111], v[60:63], v[220:223], v[108:111]
	v_mfma_f32_16x16x32_bf16 v[104:107], v[68:71], v[220:223], v[104:107]
	v_mfma_f32_16x16x32_bf16 v[144:147], v[72:75], v[180:183], v[144:147]
	v_mfma_f32_16x16x32_bf16 v[148:151], v[80:83], v[180:183], v[148:151]
	v_mfma_f32_16x16x32_bf16 v[128:131], v[72:75], v[200:203], v[128:131]
	v_mfma_f32_16x16x32_bf16 v[132:135], v[80:83], v[200:203], v[132:135]
	v_mfma_f32_16x16x32_bf16 v[112:115], v[72:75], v[208:211], v[112:115]
	v_mfma_f32_16x16x32_bf16 v[116:119], v[80:83], v[208:211], v[116:119]
	v_mfma_f32_16x16x32_bf16 v[96:99], v[72:75], v[216:219], v[96:99]
	v_mfma_f32_16x16x32_bf16 v[100:103], v[80:83], v[216:219], v[100:103]
	v_mfma_f32_16x16x32_bf16 v[144:147], v[76:79], v[196:199], v[144:147]
	v_mfma_f32_16x16x32_bf16 v[148:151], v[84:87], v[196:199], v[148:151]
	v_mfma_f32_16x16x32_bf16 v[128:131], v[76:79], v[204:207], v[128:131]
	v_mfma_f32_16x16x32_bf16 v[132:135], v[84:87], v[204:207], v[132:135]
	v_mfma_f32_16x16x32_bf16 v[112:115], v[76:79], v[212:215], v[112:115]
	v_mfma_f32_16x16x32_bf16 v[116:119], v[84:87], v[212:215], v[116:119]
	v_mfma_f32_16x16x32_bf16 v[96:99], v[76:79], v[220:223], v[96:99]
	v_mfma_f32_16x16x32_bf16 v[100:103], v[84:87], v[220:223], v[100:103]
	s_barrier
	s_setprio 0
	s_add_i32 s3, s3, s19
	v_lshl_add_u64 v[224:225], v[224:225], 0, s[40:41]
	s_mov_b32 m0, s3
	ds_read_b128 v[180:183], v190 offset:49152
	ds_read_b128 v[196:199], v190 offset:50176
	ds_read_b128 v[200:203], v190 offset:51200
	ds_read_b128 v[204:207], v190 offset:52224
	ds_read_b128 v[208:211], v190 offset:53248
	ds_read_b128 v[212:215], v190 offset:54272
	ds_read_b128 v[216:219], v190 offset:55296
	ds_read_b128 v[220:223], v190 offset:56320
	global_load_lds_dwordx4 v[224:225], off
	s_add_i32 m0, s3, 0x2000
	s_add_u32 s14, s62, 0x100800
	v_lshl_add_u64 v[224:225], v[228:229], 0, s[40:41]
	s_addc_u32 s15, s63, 0
	s_add_i32 s3, s16, s19
	global_load_lds_dwordx4 v[224:225], off
	v_lshl_add_u64 v[224:225], s[14:15], 0, v[162:163]
	s_mov_b32 m0, s3
	s_nop 0
	global_load_lds_dwordx4 v[224:225], off
	v_lshl_add_u64 v[224:225], s[14:15], 0, v[166:167]
	s_add_i32 m0, s3, 0x2000
	s_nop 0
	global_load_lds_dwordx4 v[224:225], off
	v_lshl_add_u64 v[224:225], v[230:231], 0, s[40:41]
	s_mov_b32 m0, s75
	s_nop 0
	global_load_lds_dwordx4 v[224:225], off
	v_lshl_add_u64 v[224:225], v[232:233], 0, s[40:41]
	s_mov_b32 m0, s76
	s_nop 0
	global_load_lds_dwordx4 v[224:225], off
	s_waitcnt vmcnt(8)
	s_waitcnt lgkmcnt(0)
	s_setprio 1
	s_barrier
	v_mfma_f32_16x16x32_bf16 v[92:95], v[56:59], v[180:183], v[92:95]
	v_mfma_f32_16x16x32_bf16 v[88:91], v[64:67], v[180:183], v[88:91]
	v_mfma_f32_16x16x32_bf16 v[44:47], v[56:59], v[200:203], v[44:47]
	v_mfma_f32_16x16x32_bf16 v[40:43], v[64:67], v[200:203], v[40:43]
	v_mfma_f32_16x16x32_bf16 v[28:31], v[56:59], v[208:211], v[28:31]
	v_mfma_f32_16x16x32_bf16 v[24:27], v[64:67], v[208:211], v[24:27]
	v_mfma_f32_16x16x32_bf16 v[12:15], v[56:59], v[216:219], v[12:15]
	v_mfma_f32_16x16x32_bf16 v[8:11], v[64:67], v[216:219], v[8:11]
	v_mfma_f32_16x16x32_bf16 v[92:95], v[60:63], v[196:199], v[92:95]
	v_mfma_f32_16x16x32_bf16 v[88:91], v[68:71], v[196:199], v[88:91]
	v_mfma_f32_16x16x32_bf16 v[44:47], v[60:63], v[204:207], v[44:47]
	v_mfma_f32_16x16x32_bf16 v[40:43], v[68:71], v[204:207], v[40:43]
	v_mfma_f32_16x16x32_bf16 v[28:31], v[60:63], v[212:215], v[28:31]
	v_mfma_f32_16x16x32_bf16 v[24:27], v[68:71], v[212:215], v[24:27]
	v_mfma_f32_16x16x32_bf16 v[12:15], v[60:63], v[220:223], v[12:15]
	v_mfma_f32_16x16x32_bf16 v[8:11], v[68:71], v[220:223], v[8:11]
	v_mfma_f32_16x16x32_bf16 v[48:51], v[72:75], v[180:183], v[48:51]
	v_mfma_f32_16x16x32_bf16 v[52:55], v[80:83], v[180:183], v[52:55]
	v_mfma_f32_16x16x32_bf16 v[32:35], v[72:75], v[200:203], v[32:35]
	v_mfma_f32_16x16x32_bf16 v[36:39], v[80:83], v[200:203], v[36:39]
	v_mfma_f32_16x16x32_bf16 v[16:19], v[72:75], v[208:211], v[16:19]
	v_mfma_f32_16x16x32_bf16 v[20:23], v[80:83], v[208:211], v[20:23]
	v_mfma_f32_16x16x32_bf16 v[0:3], v[72:75], v[216:219], v[0:3]
	v_mfma_f32_16x16x32_bf16 v[4:7], v[80:83], v[216:219], v[4:7]
	v_mfma_f32_16x16x32_bf16 v[48:51], v[76:79], v[196:199], v[48:51]
	v_mfma_f32_16x16x32_bf16 v[68:71], v[84:87], v[196:199], v[52:55]
	v_mfma_f32_16x16x32_bf16 v[32:35], v[76:79], v[204:207], v[32:35]
	v_mfma_f32_16x16x32_bf16 v[36:39], v[84:87], v[204:207], v[36:39]
	v_mfma_f32_16x16x32_bf16 v[16:19], v[76:79], v[212:215], v[16:19]
	v_mfma_f32_16x16x32_bf16 v[20:23], v[84:87], v[212:215], v[20:23]
	v_mfma_f32_16x16x32_bf16 v[0:3], v[76:79], v[220:223], v[0:3]
	v_mfma_f32_16x16x32_bf16 v[4:7], v[84:87], v[220:223], v[4:7]
	s_barrier
	s_setprio 0
	s_add_i32 s93, s93, 2
	s_add_u32 s90, s90, 0x1000
	s_addc_u32 s91, s91, 0
	s_cmp_gt_u32 s93, 61
	s_mov_b64 s[14:15], s[60:61]
	s_cbranch_scc0 .LBB0_639
	s_and_b64 vcc, exec, s[42:43]
	s_cbranch_vccz .LBB0_642
	s_barrier

.LBB0_771:
	ds_read_b128 v[128:131], v188
	ds_read_b128 v[132:135], v188 offset:1024
	ds_read_b128 v[136:139], v188 offset:2048
	ds_read_b128 v[140:143], v188 offset:3072
	ds_read_b128 v[144:147], v189
	ds_read_b128 v[148:151], v189 offset:1024
	ds_read_b128 v[166:169], v189 offset:2048
	ds_read_b128 v[170:173], v189 offset:3072
	s_add_u32 s3, s38, 0xffd50800
	s_addc_u32 s16, s39, -1
	s_cmpk_eq_i32 s68, 0xa8
	s_cselect_b32 s43, s7, s16
	s_cselect_b32 s42, s6, s3
	s_cselect_b32 s41, s21, s67
	s_cselect_b32 s40, s20, s66
	v_lshl_add_u64 v[192:193], s[38:39], 0, v[158:159]
	s_add_i32 m0, s44, 0xc000
	ds_read_b128 v[174:177], v190
	ds_read_b128 v[178:181], v190 offset:1024
	ds_read_b128 v[182:185], v190 offset:2048
	ds_read_b128 v[196:199], v190 offset:3072
	ds_read_b128 v[200:203], v190 offset:4096
	ds_read_b128 v[204:207], v190 offset:5120
	ds_read_b128 v[208:211], v190 offset:6144
	ds_read_b128 v[212:215], v190 offset:7168
	global_load_lds_dwordx4 v[192:193], off
	v_lshl_add_u64 v[192:193], s[38:39], 0, v[160:161]
	s_add_i32 m0, s44, 0xe000
	s_nop 0
	global_load_lds_dwordx4 v[192:193], off
	s_waitcnt vmcnt(8)
	s_waitcnt lgkmcnt(0)
	s_setprio 1
	s_barrier
	v_mfma_f32_16x16x32_bf16 v[124:127], v[128:131], v[174:177], v[124:127]
	v_mfma_f32_16x16x32_bf16 v[120:123], v[136:139], v[174:177], v[120:123]
	v_mfma_f32_16x16x32_bf16 v[108:111], v[128:131], v[182:185], v[108:111]
	v_mfma_f32_16x16x32_bf16 v[104:107], v[136:139], v[182:185], v[104:107]
	v_mfma_f32_16x16x32_bf16 v[92:95], v[128:131], v[200:203], v[92:95]
	v_mfma_f32_16x16x32_bf16 v[88:91], v[136:139], v[200:203], v[88:91]
	v_mfma_f32_16x16x32_bf16 v[76:79], v[128:131], v[208:211], v[76:79]
	v_mfma_f32_16x16x32_bf16 v[72:75], v[136:139], v[208:211], v[72:75]
	v_mfma_f32_16x16x32_bf16 v[124:127], v[132:135], v[178:181], v[124:127]
	v_mfma_f32_16x16x32_bf16 v[120:123], v[140:143], v[178:181], v[120:123]
	v_mfma_f32_16x16x32_bf16 v[108:111], v[132:135], v[196:199], v[108:111]
	v_mfma_f32_16x16x32_bf16 v[104:107], v[140:143], v[196:199], v[104:107]
	v_mfma_f32_16x16x32_bf16 v[92:95], v[132:135], v[204:207], v[92:95]
	v_mfma_f32_16x16x32_bf16 v[88:91], v[140:143], v[204:207], v[88:91]
	v_mfma_f32_16x16x32_bf16 v[76:79], v[132:135], v[212:215], v[76:79]
	v_mfma_f32_16x16x32_bf16 v[72:75], v[140:143], v[212:215], v[72:75]
	v_mfma_f32_16x16x32_bf16 v[116:119], v[144:147], v[174:177], v[116:119]
	v_mfma_f32_16x16x32_bf16 v[112:115], v[166:169], v[174:177], v[112:115]
	v_mfma_f32_16x16x32_bf16 v[100:103], v[144:147], v[182:185], v[100:103]
	v_mfma_f32_16x16x32_bf16 v[96:99], v[166:169], v[182:185], v[96:99]
	v_mfma_f32_16x16x32_bf16 v[84:87], v[144:147], v[200:203], v[84:87]
	v_mfma_f32_16x16x32_bf16 v[80:83], v[166:169], v[200:203], v[80:83]
	v_mfma_f32_16x16x32_bf16 v[68:71], v[144:147], v[208:211], v[68:71]
	v_mfma_f32_16x16x32_bf16 v[64:67], v[166:169], v[208:211], v[64:67]
	v_mfma_f32_16x16x32_bf16 v[116:119], v[148:151], v[178:181], v[116:119]
	v_mfma_f32_16x16x32_bf16 v[112:115], v[170:173], v[178:181], v[112:115]
	v_mfma_f32_16x16x32_bf16 v[100:103], v[148:151], v[196:199], v[100:103]
	v_mfma_f32_16x16x32_bf16 v[96:99], v[170:173], v[196:199], v[96:99]
	v_mfma_f32_16x16x32_bf16 v[84:87], v[148:151], v[204:207], v[84:87]
	v_mfma_f32_16x16x32_bf16 v[80:83], v[170:173], v[204:207], v[80:83]
	v_mfma_f32_16x16x32_bf16 v[68:71], v[148:151], v[212:215], v[68:71]
	v_mfma_f32_16x16x32_bf16 v[64:67], v[170:173], v[212:215], v[64:67]
	s_barrier
	s_setprio 0
	s_add_i32 s3, s55, s19
	v_lshl_add_u64 v[192:193], s[40:41], 0, v[152:153]
	s_mov_b32 m0, s3
	ds_read_b128 v[174:177], v190 offset:16384
	ds_read_b128 v[178:181], v190 offset:17408
	ds_read_b128 v[182:185], v190 offset:18432
	ds_read_b128 v[196:199], v190 offset:19456
	ds_read_b128 v[200:203], v190 offset:20480
	ds_read_b128 v[204:207], v190 offset:21504
	ds_read_b128 v[208:211], v190 offset:22528
	ds_read_b128 v[212:215], v190 offset:23552
	global_load_lds_dwordx4 v[192:193], off
	s_add_i32 m0, s3, 0x2000
	s_add_u32 s16, s40, 0x2b0000
	v_lshl_add_u64 v[216:217], s[40:41], 0, v[154:155]
	s_addc_u32 s17, s41, 0
	s_add_i32 s3, s56, s19
	global_load_lds_dwordx4 v[216:217], off
	v_lshl_add_u64 v[218:219], s[16:17], 0, v[152:153]
	s_mov_b32 m0, s3
	v_lshl_add_u64 v[220:221], s[42:43], 0, v[154:155]
	global_load_lds_dwordx4 v[218:219], off
	v_lshl_add_u64 v[218:219], s[16:17], 0, v[154:155]
	s_add_i32 m0, s3, 0x2000
	s_nop 0
	global_load_lds_dwordx4 v[218:219], off
	v_lshl_add_u64 v[218:219], s[42:43], 0, v[152:153]
	s_mov_b32 m0, s44
	s_nop 0
	global_load_lds_dwordx4 v[218:219], off
	s_mov_b32 m0, s45
	s_nop 0
	global_load_lds_dwordx4 v[220:221], off
	s_waitcnt vmcnt(8)
	s_waitcnt lgkmcnt(0)
	s_setprio 1
	s_barrier
	v_mfma_f32_16x16x32_bf16 v[60:63], v[128:131], v[174:177], v[60:63]
	v_mfma_f32_16x16x32_bf16 v[56:59], v[136:139], v[174:177], v[56:59]
	v_mfma_f32_16x16x32_bf16 v[44:47], v[128:131], v[182:185], v[44:47]
	v_mfma_f32_16x16x32_bf16 v[40:43], v[136:139], v[182:185], v[40:43]
	v_mfma_f32_16x16x32_bf16 v[28:31], v[128:131], v[200:203], v[28:31]
	v_mfma_f32_16x16x32_bf16 v[24:27], v[136:139], v[200:203], v[24:27]
	v_mfma_f32_16x16x32_bf16 v[12:15], v[128:131], v[208:211], v[12:15]
	v_mfma_f32_16x16x32_bf16 v[8:11], v[136:139], v[208:211], v[8:11]
	v_mfma_f32_16x16x32_bf16 v[60:63], v[132:135], v[178:181], v[60:63]
	v_mfma_f32_16x16x32_bf16 v[56:59], v[140:143], v[178:181], v[56:59]
	v_mfma_f32_16x16x32_bf16 v[44:47], v[132:135], v[196:199], v[44:47]
	v_mfma_f32_16x16x32_bf16 v[40:43], v[140:143], v[196:199], v[40:43]
	v_mfma_f32_16x16x32_bf16 v[28:31], v[132:135], v[204:207], v[28:31]
	v_mfma_f32_16x16x32_bf16 v[24:27], v[140:143], v[204:207], v[24:27]
	v_mfma_f32_16x16x32_bf16 v[12:15], v[132:135], v[212:215], v[12:15]
	v_mfma_f32_16x16x32_bf16 v[8:11], v[140:143], v[212:215], v[8:11]
	v_mfma_f32_16x16x32_bf16 v[52:55], v[144:147], v[174:177], v[52:55]
	v_mfma_f32_16x16x32_bf16 v[48:51], v[166:169], v[174:177], v[48:51]
	v_mfma_f32_16x16x32_bf16 v[36:39], v[144:147], v[182:185], v[36:39]
	v_mfma_f32_16x16x32_bf16 v[32:35], v[166:169], v[182:185], v[32:35]
	v_mfma_f32_16x16x32_bf16 v[20:23], v[144:147], v[200:203], v[20:23]
	v_mfma_f32_16x16x32_bf16 v[16:19], v[166:169], v[200:203], v[16:19]
	v_mfma_f32_16x16x32_bf16 v[4:7], v[144:147], v[208:211], v[4:7]
	v_mfma_f32_16x16x32_bf16 v[0:3], v[166:169], v[208:211], v[0:3]
	v_mfma_f32_16x16x32_bf16 v[52:55], v[148:151], v[178:181], v[52:55]
	v_mfma_f32_16x16x32_bf16 v[48:51], v[170:173], v[178:181], v[48:51]
	v_mfma_f32_16x16x32_bf16 v[36:39], v[148:151], v[196:199], v[36:39]
	v_mfma_f32_16x16x32_bf16 v[32:35], v[170:173], v[196:199], v[32:35]
	v_mfma_f32_16x16x32_bf16 v[20:23], v[148:151], v[204:207], v[20:23]
	v_mfma_f32_16x16x32_bf16 v[16:19], v[170:173], v[204:207], v[16:19]
	v_mfma_f32_16x16x32_bf16 v[4:7], v[148:151], v[212:215], v[4:7]
	v_mfma_f32_16x16x32_bf16 v[0:3], v[170:173], v[212:215], v[0:3]
	s_barrier
	s_setprio 0
	s_add_i32 s3, 0, 0x18000
	s_add_i32 s33, 0, 0x1c000
	v_add_u32_e32 v140, s3, v187
	v_add_u32_e32 v170, s33, v187
	ds_read_b128 v[128:131], v140
	ds_read_b128 v[132:135], v140 offset:1024
	ds_read_b128 v[136:139], v140 offset:2048
	ds_read_b128 v[140:143], v140 offset:3072
	ds_read_b128 v[144:147], v170
	ds_read_b128 v[148:151], v170 offset:1024
	ds_read_b128 v[166:169], v170 offset:2048
	ds_read_b128 v[170:173], v170 offset:3072
	s_add_u32 s16, s42, 0x2b0000
	s_addc_u32 s17, s43, 0
	s_mov_b32 m0, s46
	v_lshl_add_u64 v[222:223], s[16:17], 0, v[152:153]
	ds_read_b128 v[174:177], v190 offset:32768
	ds_read_b128 v[178:181], v190 offset:33792
	ds_read_b128 v[182:185], v190 offset:34816
	ds_read_b128 v[196:199], v190 offset:35840
	ds_read_b128 v[200:203], v190 offset:36864
	ds_read_b128 v[204:207], v190 offset:37888
	ds_read_b128 v[208:211], v190 offset:38912
	ds_read_b128 v[212:215], v190 offset:39936
	global_load_lds_dwordx4 v[222:223], off
	v_lshl_add_u64 v[222:223], s[16:17], 0, v[154:155]
	s_mov_b32 m0, s47
	s_nop 0
	global_load_lds_dwordx4 v[222:223], off
	s_waitcnt vmcnt(8)
	s_waitcnt lgkmcnt(0)
	s_setprio 1
	s_barrier
	v_mfma_f32_16x16x32_bf16 v[124:127], v[128:131], v[174:177], v[124:127]
	v_mfma_f32_16x16x32_bf16 v[120:123], v[136:139], v[174:177], v[120:123]
	v_mfma_f32_16x16x32_bf16 v[108:111], v[128:131], v[182:185], v[108:111]
	v_mfma_f32_16x16x32_bf16 v[104:107], v[136:139], v[182:185], v[104:107]
	v_mfma_f32_16x16x32_bf16 v[92:95], v[128:131], v[200:203], v[92:95]
	v_mfma_f32_16x16x32_bf16 v[88:91], v[136:139], v[200:203], v[88:91]
	v_mfma_f32_16x16x32_bf16 v[76:79], v[128:131], v[208:211], v[76:79]
	v_mfma_f32_16x16x32_bf16 v[72:75], v[136:139], v[208:211], v[72:75]
	v_mfma_f32_16x16x32_bf16 v[124:127], v[132:135], v[178:181], v[124:127]
	v_mfma_f32_16x16x32_bf16 v[120:123], v[140:143], v[178:181], v[120:123]
	v_mfma_f32_16x16x32_bf16 v[108:111], v[132:135], v[196:199], v[108:111]
	v_mfma_f32_16x16x32_bf16 v[104:107], v[140:143], v[196:199], v[104:107]
	v_mfma_f32_16x16x32_bf16 v[92:95], v[132:135], v[204:207], v[92:95]
	v_mfma_f32_16x16x32_bf16 v[88:91], v[140:143], v[204:207], v[88:91]
	v_mfma_f32_16x16x32_bf16 v[76:79], v[132:135], v[212:215], v[76:79]
	v_mfma_f32_16x16x32_bf16 v[72:75], v[140:143], v[212:215], v[72:75]
	v_mfma_f32_16x16x32_bf16 v[116:119], v[144:147], v[174:177], v[116:119]
	v_mfma_f32_16x16x32_bf16 v[112:115], v[166:169], v[174:177], v[112:115]
	v_mfma_f32_16x16x32_bf16 v[100:103], v[144:147], v[182:185], v[100:103]
	v_mfma_f32_16x16x32_bf16 v[96:99], v[166:169], v[182:185], v[96:99]
	v_mfma_f32_16x16x32_bf16 v[84:87], v[144:147], v[200:203], v[84:87]
	v_mfma_f32_16x16x32_bf16 v[80:83], v[166:169], v[200:203], v[80:83]
	v_mfma_f32_16x16x32_bf16 v[68:71], v[144:147], v[208:211], v[68:71]
	v_mfma_f32_16x16x32_bf16 v[64:67], v[166:169], v[208:211], v[64:67]
	v_mfma_f32_16x16x32_bf16 v[116:119], v[148:151], v[178:181], v[116:119]
	v_mfma_f32_16x16x32_bf16 v[112:115], v[170:173], v[178:181], v[112:115]
	v_mfma_f32_16x16x32_bf16 v[100:103], v[148:151], v[196:199], v[100:103]
	v_mfma_f32_16x16x32_bf16 v[96:99], v[170:173], v[196:199], v[96:99]
	v_mfma_f32_16x16x32_bf16 v[84:87], v[148:151], v[204:207], v[84:87]
	v_mfma_f32_16x16x32_bf16 v[80:83], v[170:173], v[204:207], v[80:83]
	v_mfma_f32_16x16x32_bf16 v[68:71], v[148:151], v[212:215], v[68:71]
	v_mfma_f32_16x16x32_bf16 v[64:67], v[170:173], v[212:215], v[64:67]
	s_barrier
	s_setprio 0
	s_add_i32 s3, s3, s19
	v_lshl_add_u64 v[192:193], v[192:193], 0, s[12:13]
	s_mov_b32 m0, s3
	ds_read_b128 v[174:177], v190 offset:49152
	ds_read_b128 v[178:181], v190 offset:50176
	ds_read_b128 v[182:185], v190 offset:51200
	ds_read_b128 v[196:199], v190 offset:52224
	ds_read_b128 v[200:203], v190 offset:53248
	ds_read_b128 v[204:207], v190 offset:54272
	ds_read_b128 v[208:211], v190 offset:55296
	ds_read_b128 v[212:215], v190 offset:56320
	global_load_lds_dwordx4 v[192:193], off
	s_add_i32 m0, s3, 0x2000
	s_add_u32 s16, s40, 0x2b0800
	v_lshl_add_u64 v[192:193], v[216:217], 0, s[12:13]
	s_addc_u32 s17, s41, 0
	s_add_i32 s3, s33, s19
	global_load_lds_dwordx4 v[192:193], off
	v_lshl_add_u64 v[192:193], s[16:17], 0, v[152:153]
	s_mov_b32 m0, s3
	s_nop 0
	global_load_lds_dwordx4 v[192:193], off
	v_lshl_add_u64 v[192:193], s[16:17], 0, v[154:155]
	s_add_i32 m0, s3, 0x2000
	s_nop 0
	global_load_lds_dwordx4 v[192:193], off
	v_lshl_add_u64 v[192:193], v[218:219], 0, s[12:13]
	s_mov_b32 m0, s50
	s_nop 0
	global_load_lds_dwordx4 v[192:193], off
	v_lshl_add_u64 v[192:193], v[220:221], 0, s[12:13]
	s_mov_b32 m0, s51
	s_nop 0
	global_load_lds_dwordx4 v[192:193], off
	s_waitcnt vmcnt(8)
	s_waitcnt lgkmcnt(0)
	s_setprio 1
	s_barrier
	v_mfma_f32_16x16x32_bf16 v[60:63], v[128:131], v[174:177], v[60:63]
	v_mfma_f32_16x16x32_bf16 v[56:59], v[136:139], v[174:177], v[56:59]
	v_mfma_f32_16x16x32_bf16 v[44:47], v[128:131], v[182:185], v[44:47]
	v_mfma_f32_16x16x32_bf16 v[40:43], v[136:139], v[182:185], v[40:43]
	v_mfma_f32_16x16x32_bf16 v[28:31], v[128:131], v[200:203], v[28:31]
	v_mfma_f32_16x16x32_bf16 v[24:27], v[136:139], v[200:203], v[24:27]
	v_mfma_f32_16x16x32_bf16 v[12:15], v[128:131], v[208:211], v[12:15]
	v_mfma_f32_16x16x32_bf16 v[8:11], v[136:139], v[208:211], v[8:11]
	v_mfma_f32_16x16x32_bf16 v[60:63], v[132:135], v[178:181], v[60:63]
	v_mfma_f32_16x16x32_bf16 v[56:59], v[140:143], v[178:181], v[56:59]
	v_mfma_f32_16x16x32_bf16 v[44:47], v[132:135], v[196:199], v[44:47]
	v_mfma_f32_16x16x32_bf16 v[40:43], v[140:143], v[196:199], v[40:43]
	v_mfma_f32_16x16x32_bf16 v[28:31], v[132:135], v[204:207], v[28:31]
	v_mfma_f32_16x16x32_bf16 v[24:27], v[140:143], v[204:207], v[24:27]
	v_mfma_f32_16x16x32_bf16 v[12:15], v[132:135], v[212:215], v[12:15]
	v_mfma_f32_16x16x32_bf16 v[8:11], v[140:143], v[212:215], v[8:11]
	v_mfma_f32_16x16x32_bf16 v[52:55], v[144:147], v[174:177], v[52:55]
	v_mfma_f32_16x16x32_bf16 v[48:51], v[166:169], v[174:177], v[48:51]
	v_mfma_f32_16x16x32_bf16 v[36:39], v[144:147], v[182:185], v[36:39]
	v_mfma_f32_16x16x32_bf16 v[32:35], v[166:169], v[182:185], v[32:35]
	v_mfma_f32_16x16x32_bf16 v[20:23], v[144:147], v[200:203], v[20:23]
	v_mfma_f32_16x16x32_bf16 v[16:19], v[166:169], v[200:203], v[16:19]
	v_mfma_f32_16x16x32_bf16 v[4:7], v[144:147], v[208:211], v[4:7]
	v_mfma_f32_16x16x32_bf16 v[0:3], v[166:169], v[208:211], v[0:3]
	v_mfma_f32_16x16x32_bf16 v[52:55], v[148:151], v[178:181], v[52:55]
	v_mfma_f32_16x16x32_bf16 v[48:51], v[170:173], v[178:181], v[48:51]
	v_mfma_f32_16x16x32_bf16 v[36:39], v[148:151], v[196:199], v[36:39]
	v_mfma_f32_16x16x32_bf16 v[32:35], v[170:173], v[196:199], v[32:35]
	v_mfma_f32_16x16x32_bf16 v[20:23], v[148:151], v[204:207], v[20:23]
	v_mfma_f32_16x16x32_bf16 v[16:19], v[170:173], v[204:207], v[16:19]
	v_mfma_f32_16x16x32_bf16 v[4:7], v[148:151], v[212:215], v[4:7]
	v_mfma_f32_16x16x32_bf16 v[0:3], v[170:173], v[212:215], v[0:3]
	s_barrier
	s_setprio 0
	s_add_i32 s68, s68, 2
	s_add_u32 s38, s38, 0x1000
	s_addc_u32 s39, s39, 0
	s_add_u32 s66, s66, 0x1000
	s_addc_u32 s67, s67, 0
	s_cmpk_gt_u32 s68, 0xa9
	s_cbranch_scc0 .LBB0_771
	s_and_b64 vcc, exec, s[14:15]
	s_cbranch_vccz .LBB0_774
	s_barrier
